# k41 + residual tiles of the P2/P5/P7 EpiRes epilogues staged through LDS by full-line LDS-DMA in two pipelined halves (packed-f32 epilogue math), sc1 on ACT stores
# baseline (speedup 1.0000x reference)
; __device__ __forceinline__ unsigned cvt_pk_bf16(float lo, float hi) { unsigned r; asm volatile("v_cvt_pk_bf16_f32 %0, %1, %2" : "=v"(r) : "v"(lo), "v"(hi)); return r; }
;     __device__ __forceinline__ void operator()(const f32x4 (&acc)[2][2][4][2], const Unit& u, int wr, int wc, int fr, int fq) const {
;         const int row0 = u.pm * BM + wr * 64 + fr, col0 = u.pn * BM + wc * 32 + 8 * fq;
;         u32x4 rb[2][4][2];
; #pragma unroll
;         for (int ai = 0; ai < 2; ++ai)
; #pragma unroll
;             for (int m = 0; m < 4; ++m) { const bf16_t* xq = XB + (size_t)(row0 + ai * HALF + m * 16) * 1024 + col0; rb[ai][m][0] = *(const u32x4*)xq; rb[ai][m][1] = *(const u32x4*)(xq + HALF); }
; #pragma unroll
;         for (int ai = 0; ai < 2; ++ai) {
; #pragma unroll
;             for (int m = 0; m < 4; ++m) {
;                 const int r = row0 + ai * HALF + m * 16;
;                 bf16_t* xp = XB + (size_t)r * 1024 + col0;
;                 const u32x4 b0 = rb[ai][m][0], b1 = rb[ai][m][1];
;                 float ss = 0.f;
; #pragma unroll
;                 for (int bj = 0; bj < 2; ++bj) {
;                     const u32x4 b = bj ? b1 : b0;
;                     f32x4 v0, v1;
;                     v0[0] = __uint_as_float(b.x << 16); v0[1] = __uint_as_float(b.x & 0xffff0000u); v0[2] = __uint_as_float(b.y << 16); v0[3] = __uint_as_float(b.y & 0xffff0000u);
;                     v1[0] = __uint_as_float(b.z << 16); v1[1] = __uint_as_float(b.z & 0xffff0000u); v1[2] = __uint_as_float(b.w << 16); v1[3] = __uint_as_float(b.w & 0xffff0000u);
;                     v0 += acc[ai][bj][m][0] * alpha; v1 += acc[ai][bj][m][1] * alpha;
;                     ss += (v0[0] * v0[0] + v0[1] * v0[1]) + (v0[2] * v0[2] + v0[3] * v0[3]) + (v1[0] * v1[0] + v1[1] * v1[1]) + (v1[2] * v1[2] + v1[3] * v1[3]);
;                     u32x4 w; w.x = cvt_pk_bf16(v0[0], v0[1]); w.y = cvt_pk_bf16(v0[2], v0[3]); w.z = cvt_pk_bf16(v1[0], v1[1]); w.w = cvt_pk_bf16(v1[2], v1[3]);
;                     *(u32x4*)(xp + bj * HALF) = w;
;                 }
;                 ss += __shfl_xor(ss, 16); ss += __shfl_xor(ss, 32);
;                 if (fq == 0) SS[(size_t)r * 16 + u.pn * 4 + wc] = ss;
;             }
;         }
;     }
.LBB0_372:
	v_lshl_or_b32 v144, s20, 8, v246
	v_lshl_add_u32 v146, s48, 8, v129
	v_lshlrev_b32_e32 v144, 1, v144
	v_mov_b32_e32 v145, 0
	v_mov_b32_e32 v147, 0
	s_mov_b32 s84, 0x8000
	s_mov_b32 s85, 0
	s_mov_b32 s86, 0x40000
	s_mov_b32 s87, 0
	v_lshl_add_u64 v[148:149], s[34:35], 0, v[144:145]
	v_lshlrev_b32_e32 v236, 11, v146
	v_mov_b32_e32 v237, 0
	v_lshl_add_u64 v[148:149], v[148:149], 0, v[236:237]
	v_lshl_add_u64 v[156:157], v[148:149], 0, s[86:87]
	v_lshl_add_u64 v[150:151], v[148:149], 0, s[84:85]
	v_lshl_add_u64 v[152:153], v[150:151], 0, s[84:85]
	v_lshl_add_u64 v[154:155], v[152:153], 0, s[84:85]
	v_lshl_add_u64 v[160:161], v[156:157], 0, s[84:85]
	v_lshl_add_u64 v[162:163], v[160:161], 0, s[84:85]
	v_lshl_add_u64 v[164:165], v[162:163], 0, s[84:85]
	v_readfirstlane_b32 s101, v192
	s_nop 1
	s_lshr_b32 s101, s101, 6
	v_lshrrev_b32_e32 v240, 5, v247
	v_and_b32_e32 v241, 31, v247
	v_mov_b32_e32 v242, v240
	v_xor_b32_e32 v243, v241, v242
	v_lshlrev_b32_e32 v243, 4, v243
	v_lshl_add_u32 v172, v242, 11, v243
	v_or_b32_e32 v242, 2, v240
	v_xor_b32_e32 v243, v241, v242
	v_lshlrev_b32_e32 v243, 4, v243
	v_lshl_add_u32 v180, v242, 11, v243
	v_or_b32_e32 v242, 4, v240
	v_xor_b32_e32 v243, v241, v242
	v_lshlrev_b32_e32 v243, 4, v243
	v_lshl_add_u32 v188, v242, 11, v243
	v_or_b32_e32 v242, 6, v240
	v_xor_b32_e32 v243, v241, v242
	v_lshlrev_b32_e32 v243, 4, v243
	v_lshl_add_u32 v200, v242, 11, v243
	v_or_b32_e32 v242, 8, v240
	v_xor_b32_e32 v243, v241, v242
	v_lshlrev_b32_e32 v243, 4, v243
	v_lshl_add_u32 v208, v242, 11, v243
	v_or_b32_e32 v242, 10, v240
	v_xor_b32_e32 v243, v241, v242
	v_lshlrev_b32_e32 v243, 4, v243
	v_lshl_add_u32 v216, v242, 11, v243
	v_or_b32_e32 v242, 12, v240
	v_xor_b32_e32 v243, v241, v242
	v_lshlrev_b32_e32 v243, 4, v243
	v_lshl_add_u32 v224, v242, 11, v243
	v_or_b32_e32 v242, 14, v240
	v_xor_b32_e32 v243, v241, v242
	v_lshlrev_b32_e32 v243, 4, v243
	v_lshl_add_u32 v232, v242, 11, v243
	s_lshl_b32 s98, s48, 19
	s_lshl_b32 s99, s101, 15
	s_add_u32 s98, s98, s99
	s_lshl_b32 s99, s20, 9
	s_add_u32 s98, s98, s99
	s_add_u32 s98, s34, s98
	s_addc_u32 s99, s35, 0
	s_lshl_b32 s100, s101, 13
	s_waitcnt vmcnt(0)
	s_barrier
	s_add_i32 m0, s100, 0x0
	s_nop 0
	global_load_lds_dwordx4 v172, s[98:99]
	s_add_i32 m0, s100, 0x400
	s_nop 0
	global_load_lds_dwordx4 v180, s[98:99]
	s_add_i32 m0, s100, 0x800
	s_nop 0
	global_load_lds_dwordx4 v188, s[98:99]
	s_add_i32 m0, s100, 0xc00
	s_nop 0
	global_load_lds_dwordx4 v200, s[98:99]
	s_add_i32 m0, s100, 0x1000
	s_nop 0
	global_load_lds_dwordx4 v208, s[98:99]
	s_add_i32 m0, s100, 0x1400
	s_nop 0
	global_load_lds_dwordx4 v216, s[98:99]
	s_add_i32 m0, s100, 0x1800
	s_nop 0
	global_load_lds_dwordx4 v224, s[98:99]
	s_add_i32 m0, s100, 0x1c00
	s_nop 0
	global_load_lds_dwordx4 v232, s[98:99]
	s_add_u32 s98, s98, 0x40000
	s_addc_u32 s99, s99, 0
	s_add_i32 m0, s100, 0x10000
	s_nop 0
	global_load_lds_dwordx4 v172, s[98:99]
	s_add_i32 m0, s100, 0x10400
	s_nop 0
	global_load_lds_dwordx4 v180, s[98:99]
	s_add_i32 m0, s100, 0x10800
	s_nop 0
	global_load_lds_dwordx4 v188, s[98:99]
	s_add_i32 m0, s100, 0x10c00
	s_nop 0
	global_load_lds_dwordx4 v200, s[98:99]
	s_add_i32 m0, s100, 0x11000
	s_nop 0
	global_load_lds_dwordx4 v208, s[98:99]
	s_add_i32 m0, s100, 0x11400
	s_nop 0
	global_load_lds_dwordx4 v216, s[98:99]
	s_add_i32 m0, s100, 0x11800
	s_nop 0
	global_load_lds_dwordx4 v224, s[98:99]
	s_add_i32 m0, s100, 0x11c00
	s_nop 0
	global_load_lds_dwordx4 v232, s[98:99]
	v_lshrrev_b32_e32 v238, 3, v246
	v_and_b32_e32 v239, 15, v129
	v_xor_b32_e32 v238, v238, v239
	v_lshlrev_b32_e32 v238, 4, v238
	v_lshl_add_u32 v236, v129, 9, v238
	v_add_u32_e32 v244, 0x10000, v236
	s_waitcnt vmcnt(8)
	s_barrier
	ds_read_b128 v[168:171], v236
	ds_read_b128 v[172:175], v236 offset:256
	ds_read_b128 v[176:179], v236 offset:8192
	ds_read_b128 v[180:183], v236 offset:8448
	ds_read_b128 v[184:187], v236 offset:16384
	ds_read_b128 v[188:191], v236 offset:16640
	ds_read_b128 v[196:199], v236 offset:24576
	ds_read_b128 v[200:203], v236 offset:24832
	s_waitcnt lgkmcnt(0)
	v_xor_b32_e32 v128, 16, v247
	v_xor_b32_e32 v158, 32, v247
	v_lshlrev_b32_e32 v128, 2, v128
	v_lshlrev_b32_e32 v158, 2, v158
	s_lshl_b32 s90, s20, 2
	s_add_i32 s90, s90, s66
	s_lshl_b32 s90, s90, 2
	s_mov_b32 s91, 0
	v_lshlrev_b32_e32 v238, 6, v146
	v_mov_b32_e32 v239, 0
	v_lshl_add_u64 v[194:195], s[44:45], 0, v[238:239]
	v_lshl_add_u64 v[194:195], v[194:195], 0, s[90:91]
	v_lshlrev_b32_e32 v236, 16, v168
	v_and_b32_e32 v237, 0xffff0000, v168
	v_lshlrev_b32_e32 v238, 16, v169
	v_and_b32_e32 v239, 0xffff0000, v169
	v_lshlrev_b32_e32 v240, 16, v170
	v_and_b32_e32 v241, 0xffff0000, v170
	v_lshlrev_b32_e32 v242, 16, v171
	v_and_b32_e32 v243, 0xffff0000, v171
	v_pk_fma_f32 v[124:125], v[124:125], 0.5, v[236:237] op_sel_hi:[1,0,1]
	v_pk_fma_f32 v[126:127], v[126:127], 0.5, v[238:239] op_sel_hi:[1,0,1]
	v_pk_fma_f32 v[120:121], v[120:121], 0.5, v[240:241] op_sel_hi:[1,0,1]
	v_pk_fma_f32 v[122:123], v[122:123], 0.5, v[242:243] op_sel_hi:[1,0,1]
	v_pk_mul_f32 v[166:167], v[124:125], v[124:125]
	v_pk_fma_f32 v[166:167], v[126:127], v[126:127], v[166:167]
	v_pk_fma_f32 v[166:167], v[120:121], v[120:121], v[166:167]
	v_pk_fma_f32 v[166:167], v[122:123], v[122:123], v[166:167]
	v_cvt_pk_bf16_f32 v168, v124, v125
	v_cvt_pk_bf16_f32 v169, v126, v127
	v_cvt_pk_bf16_f32 v170, v120, v121
	v_cvt_pk_bf16_f32 v171, v122, v123
	global_store_dwordx4 v[148:149], v[168:171], off
	v_lshlrev_b32_e32 v236, 16, v172
	v_and_b32_e32 v237, 0xffff0000, v172
	v_lshlrev_b32_e32 v238, 16, v173
	v_and_b32_e32 v239, 0xffff0000, v173
	v_lshlrev_b32_e32 v240, 16, v174
	v_and_b32_e32 v241, 0xffff0000, v174
; __device__ __forceinline__ unsigned cvt_pk_bf16(float lo, float hi) { unsigned r; asm volatile("v_cvt_pk_bf16_f32 %0, %1, %2" : "=v"(r) : "v"(lo), "v"(hi)); return r; }
; __device__ __forceinline__ unsigned cvt_pk_bf16(float lo, float hi) { const f32x2 v = {lo, hi}; const bf16x2_t b = __builtin_convertvector(v, bf16x2_t); return __builtin_bit_cast(unsigned, b); }
;     __device__ __forceinline__ void operator()(const f32x4 (&acc)[2][2][4][2], const Unit& u, int wr, int wc, int fr, int fq) const {
;     ...
;                 const int r = row0 + ai * HALF + m * 16;
;                 bf16_t* xp = XB + (size_t)r * 1024 + col0;
;                 const u32x4 b0 = rb[ai][m][0], b1 = rb[ai][m][1];
;                 float ss = 0.f;
; #pragma unroll
;                 for (int bj = 0; bj < 2; ++bj) {
;                     const u32x4 b = bj ? b1 : b0;
;                     f32x4 v0, v1;
;                     v0[0] = __uint_as_float(b.x << 16); v0[1] = __uint_as_float(b.x & 0xffff0000u); v0[2] = __uint_as_float(b.y << 16); v0[3] = __uint_as_float(b.y & 0xffff0000u);
;                     v1[0] = __uint_as_float(b.z << 16); v1[1] = __uint_as_float(b.z & 0xffff0000u); v1[2] = __uint_as_float(b.w << 16); v1[3] = __uint_as_float(b.w & 0xffff0000u);
;                     v0 += acc[ai][bj][m][0] * alpha; v1 += acc[ai][bj][m][1] * alpha;
;                     ss += (v0[0] * v0[0] + v0[1] * v0[1]) + (v0[2] * v0[2] + v0[3] * v0[3]) + (v1[0] * v1[0] + v1[1] * v1[1]) + (v1[2] * v1[2] + v1[3] * v1[3]);
;                     u32x4 w; w.x = cvt_pk_bf16(v0[0], v0[1]); w.y = cvt_pk_bf16(v0[2], v0[3]); w.z = cvt_pk_bf16(v1[0], v1[1]); w.w = cvt_pk_bf16(v1[2], v1[3]);
;                     *(u32x4*)(xp + bj * HALF) = w;
;                 }
	v_lshlrev_b32_e32 v242, 16, v175
	v_and_b32_e32 v243, 0xffff0000, v175
	v_pk_fma_f32 v[108:109], v[108:109], 0.5, v[236:237] op_sel_hi:[1,0,1]
	v_pk_fma_f32 v[110:111], v[110:111], 0.5, v[238:239] op_sel_hi:[1,0,1]
	v_pk_fma_f32 v[100:101], v[100:101], 0.5, v[240:241] op_sel_hi:[1,0,1]
	v_pk_fma_f32 v[102:103], v[102:103], 0.5, v[242:243] op_sel_hi:[1,0,1]
	v_pk_fma_f32 v[166:167], v[108:109], v[108:109], v[166:167]
	v_pk_fma_f32 v[166:167], v[110:111], v[110:111], v[166:167]
	v_pk_fma_f32 v[166:167], v[100:101], v[100:101], v[166:167]
	v_pk_fma_f32 v[166:167], v[102:103], v[102:103], v[166:167]
	v_cvt_pk_bf16_f32 v172, v108, v109
	v_cvt_pk_bf16_f32 v173, v110, v111
	v_cvt_pk_bf16_f32 v174, v100, v101
	v_cvt_pk_bf16_f32 v175, v102, v103
	global_store_dwordx4 v[148:149], v[172:175], off offset:256
	s_nop 0
	v_add_f32_e32 v148, v166, v167
	v_lshlrev_b32_e32 v236, 16, v176
	v_and_b32_e32 v237, 0xffff0000, v176
	v_lshlrev_b32_e32 v238, 16, v177
	v_and_b32_e32 v239, 0xffff0000, v177
	v_lshlrev_b32_e32 v240, 16, v178
	v_and_b32_e32 v241, 0xffff0000, v178
	v_lshlrev_b32_e32 v242, 16, v179
	v_and_b32_e32 v243, 0xffff0000, v179
	v_pk_fma_f32 v[116:117], v[116:117], 0.5, v[236:237] op_sel_hi:[1,0,1]
	v_pk_fma_f32 v[118:119], v[118:119], 0.5, v[238:239] op_sel_hi:[1,0,1]
	v_pk_fma_f32 v[112:113], v[112:113], 0.5, v[240:241] op_sel_hi:[1,0,1]
	v_pk_fma_f32 v[114:115], v[114:115], 0.5, v[242:243] op_sel_hi:[1,0,1]
	v_pk_mul_f32 v[166:167], v[116:117], v[116:117]
	v_pk_fma_f32 v[166:167], v[118:119], v[118:119], v[166:167]
	v_pk_fma_f32 v[166:167], v[112:113], v[112:113], v[166:167]
	v_pk_fma_f32 v[166:167], v[114:115], v[114:115], v[166:167]
	v_cvt_pk_bf16_f32 v176, v116, v117
	v_cvt_pk_bf16_f32 v177, v118, v119
	v_cvt_pk_bf16_f32 v178, v112, v113
	v_cvt_pk_bf16_f32 v179, v114, v115
	global_store_dwordx4 v[150:151], v[176:179], off
	v_lshlrev_b32_e32 v236, 16, v180
	v_and_b32_e32 v237, 0xffff0000, v180
	v_lshlrev_b32_e32 v238, 16, v181
	v_and_b32_e32 v239, 0xffff0000, v181
	v_lshlrev_b32_e32 v240, 16, v182
	v_and_b32_e32 v241, 0xffff0000, v182
	v_lshlrev_b32_e32 v242, 16, v183
	v_and_b32_e32 v243, 0xffff0000, v183
	v_pk_fma_f32 v[92:93], v[92:93], 0.5, v[236:237] op_sel_hi:[1,0,1]
	v_pk_fma_f32 v[94:95], v[94:95], 0.5, v[238:239] op_sel_hi:[1,0,1]
	v_pk_fma_f32 v[84:85], v[84:85], 0.5, v[240:241] op_sel_hi:[1,0,1]
	v_pk_fma_f32 v[86:87], v[86:87], 0.5, v[242:243] op_sel_hi:[1,0,1]
	v_pk_fma_f32 v[166:167], v[92:93], v[92:93], v[166:167]
	v_pk_fma_f32 v[166:167], v[94:95], v[94:95], v[166:167]
	v_pk_fma_f32 v[166:167], v[84:85], v[84:85], v[166:167]
	v_pk_fma_f32 v[166:167], v[86:87], v[86:87], v[166:167]
	v_cvt_pk_bf16_f32 v180, v92, v93
	v_cvt_pk_bf16_f32 v181, v94, v95
	v_cvt_pk_bf16_f32 v182, v84, v85
	v_cvt_pk_bf16_f32 v183, v86, v87
	global_store_dwordx4 v[150:151], v[180:183], off offset:256
	s_nop 0
	v_add_f32_e32 v150, v166, v167
	v_lshlrev_b32_e32 v236, 16, v184
	v_and_b32_e32 v237, 0xffff0000, v184
	v_lshlrev_b32_e32 v238, 16, v185
	v_and_b32_e32 v239, 0xffff0000, v185
	v_lshlrev_b32_e32 v240, 16, v186
	v_and_b32_e32 v241, 0xffff0000, v186
	v_lshlrev_b32_e32 v242, 16, v187
	v_and_b32_e32 v243, 0xffff0000, v187
	v_pk_fma_f32 v[104:105], v[104:105], 0.5, v[236:237] op_sel_hi:[1,0,1]
	v_pk_fma_f32 v[106:107], v[106:107], 0.5, v[238:239] op_sel_hi:[1,0,1]
	v_pk_fma_f32 v[96:97], v[96:97], 0.5, v[240:241] op_sel_hi:[1,0,1]
	v_pk_fma_f32 v[98:99], v[98:99], 0.5, v[242:243] op_sel_hi:[1,0,1]
	v_pk_mul_f32 v[166:167], v[104:105], v[104:105]
	v_pk_fma_f32 v[166:167], v[106:107], v[106:107], v[166:167]
	v_pk_fma_f32 v[166:167], v[96:97], v[96:97], v[166:167]
	v_pk_fma_f32 v[166:167], v[98:99], v[98:99], v[166:167]
	v_cvt_pk_bf16_f32 v184, v104, v105
	v_cvt_pk_bf16_f32 v185, v106, v107
	v_cvt_pk_bf16_f32 v186, v96, v97
	v_cvt_pk_bf16_f32 v187, v98, v99
	global_store_dwordx4 v[152:153], v[184:187], off
	v_lshlrev_b32_e32 v236, 16, v188
	v_and_b32_e32 v237, 0xffff0000, v188
	v_lshlrev_b32_e32 v238, 16, v189
	v_and_b32_e32 v239, 0xffff0000, v189
	v_lshlrev_b32_e32 v240, 16, v190
	v_and_b32_e32 v241, 0xffff0000, v190
	v_lshlrev_b32_e32 v242, 16, v191
	v_and_b32_e32 v243, 0xffff0000, v191
	v_pk_fma_f32 v[76:77], v[76:77], 0.5, v[236:237] op_sel_hi:[1,0,1]
	v_pk_fma_f32 v[78:79], v[78:79], 0.5, v[238:239] op_sel_hi:[1,0,1]
	v_pk_fma_f32 v[72:73], v[72:73], 0.5, v[240:241] op_sel_hi:[1,0,1]
	v_pk_fma_f32 v[74:75], v[74:75], 0.5, v[242:243] op_sel_hi:[1,0,1]
	v_pk_fma_f32 v[166:167], v[76:77], v[76:77], v[166:167]
	v_pk_fma_f32 v[166:167], v[78:79], v[78:79], v[166:167]
	v_pk_fma_f32 v[166:167], v[72:73], v[72:73], v[166:167]
	v_pk_fma_f32 v[166:167], v[74:75], v[74:75], v[166:167]
	v_cvt_pk_bf16_f32 v188, v76, v77
	v_cvt_pk_bf16_f32 v189, v78, v79
	v_cvt_pk_bf16_f32 v190, v72, v73
	v_cvt_pk_bf16_f32 v191, v74, v75
	global_store_dwordx4 v[152:153], v[188:191], off offset:256
	s_nop 0
	v_add_f32_e32 v152, v166, v167
	v_lshlrev_b32_e32 v236, 16, v196
	v_and_b32_e32 v237, 0xffff0000, v196
	v_lshlrev_b32_e32 v238, 16, v197
	v_and_b32_e32 v239, 0xffff0000, v197
	v_lshlrev_b32_e32 v240, 16, v198
	v_and_b32_e32 v241, 0xffff0000, v198
	v_lshlrev_b32_e32 v242, 16, v199
	v_and_b32_e32 v243, 0xffff0000, v199
	v_pk_fma_f32 v[88:89], v[88:89], 0.5, v[236:237] op_sel_hi:[1,0,1]
	v_pk_fma_f32 v[90:91], v[90:91], 0.5, v[238:239] op_sel_hi:[1,0,1]
	v_pk_fma_f32 v[80:81], v[80:81], 0.5, v[240:241] op_sel_hi:[1,0,1]
	v_pk_fma_f32 v[82:83], v[82:83], 0.5, v[242:243] op_sel_hi:[1,0,1]
	v_pk_mul_f32 v[166:167], v[88:89], v[88:89]
	v_pk_fma_f32 v[166:167], v[90:91], v[90:91], v[166:167]
	v_pk_fma_f32 v[166:167], v[80:81], v[80:81], v[166:167]
	v_pk_fma_f32 v[166:167], v[82:83], v[82:83], v[166:167]
	v_cvt_pk_bf16_f32 v196, v88, v89
	v_cvt_pk_bf16_f32 v197, v90, v91
	v_cvt_pk_bf16_f32 v198, v80, v81
	v_cvt_pk_bf16_f32 v199, v82, v83
	global_store_dwordx4 v[154:155], v[196:199], off
	v_lshlrev_b32_e32 v236, 16, v200
	v_and_b32_e32 v237, 0xffff0000, v200
	v_lshlrev_b32_e32 v238, 16, v201
	v_and_b32_e32 v239, 0xffff0000, v201
	v_lshlrev_b32_e32 v240, 16, v202
	v_and_b32_e32 v241, 0xffff0000, v202
	v_lshlrev_b32_e32 v242, 16, v203
	v_and_b32_e32 v243, 0xffff0000, v203
	v_pk_fma_f32 v[68:69], v[68:69], 0.5, v[236:237] op_sel_hi:[1,0,1]
	v_pk_fma_f32 v[70:71], v[70:71], 0.5, v[238:239] op_sel_hi:[1,0,1]
	v_pk_fma_f32 v[64:65], v[64:65], 0.5, v[240:241] op_sel_hi:[1,0,1]
	v_pk_fma_f32 v[66:67], v[66:67], 0.5, v[242:243] op_sel_hi:[1,0,1]
	v_pk_fma_f32 v[166:167], v[68:69], v[68:69], v[166:167]
	v_pk_fma_f32 v[166:167], v[70:71], v[70:71], v[166:167]
	v_pk_fma_f32 v[166:167], v[64:65], v[64:65], v[166:167]
	v_pk_fma_f32 v[166:167], v[66:67], v[66:67], v[166:167]
	v_cvt_pk_bf16_f32 v200, v68, v69
	v_cvt_pk_bf16_f32 v201, v70, v71
	v_cvt_pk_bf16_f32 v202, v64, v65
	v_cvt_pk_bf16_f32 v203, v66, v67
	global_store_dwordx4 v[154:155], v[200:203], off offset:256
	s_nop 0
	v_add_f32_e32 v154, v166, v167
	s_waitcnt vmcnt(8)
	s_barrier
; __device__ __forceinline__ unsigned cvt_pk_bf16(float lo, float hi) { unsigned r; asm volatile("v_cvt_pk_bf16_f32 %0, %1, %2" : "=v"(r) : "v"(lo), "v"(hi)); return r; }
; __device__ __forceinline__ unsigned cvt_pk_bf16(float lo, float hi) { const f32x2 v = {lo, hi}; const bf16x2_t b = __builtin_convertvector(v, bf16x2_t); return __builtin_bit_cast(unsigned, b); }
;     __device__ __forceinline__ void operator()(const f32x4 (&acc)[2][2][4][2], const Unit& u, int wr, int wc, int fr, int fq) const {
;     ...
;                 const int r = row0 + ai * HALF + m * 16;
;                 bf16_t* xp = XB + (size_t)r * 1024 + col0;
;                 const u32x4 b0 = rb[ai][m][0], b1 = rb[ai][m][1];
;                 float ss = 0.f;
; #pragma unroll
;                 for (int bj = 0; bj < 2; ++bj) {
;                     const u32x4 b = bj ? b1 : b0;
;                     f32x4 v0, v1;
;                     v0[0] = __uint_as_float(b.x << 16); v0[1] = __uint_as_float(b.x & 0xffff0000u); v0[2] = __uint_as_float(b.y << 16); v0[3] = __uint_as_float(b.y & 0xffff0000u);
;                     v1[0] = __uint_as_float(b.z << 16); v1[1] = __uint_as_float(b.z & 0xffff0000u); v1[2] = __uint_as_float(b.w << 16); v1[3] = __uint_as_float(b.w & 0xffff0000u);
;                     v0 += acc[ai][bj][m][0] * alpha; v1 += acc[ai][bj][m][1] * alpha;
;                     ss += (v0[0] * v0[0] + v0[1] * v0[1]) + (v0[2] * v0[2] + v0[3] * v0[3]) + (v1[0] * v1[0] + v1[1] * v1[1]) + (v1[2] * v1[2] + v1[3] * v1[3]);
;                     u32x4 w; w.x = cvt_pk_bf16(v0[0], v0[1]); w.y = cvt_pk_bf16(v0[2], v0[3]); w.z = cvt_pk_bf16(v1[0], v1[1]); w.w = cvt_pk_bf16(v1[2], v1[3]);
;                     *(u32x4*)(xp + bj * HALF) = w;
;                 }
	ds_read_b128 v[204:207], v244
	ds_read_b128 v[208:211], v244 offset:256
	ds_read_b128 v[212:215], v244 offset:8192
	ds_read_b128 v[216:219], v244 offset:8448
	ds_read_b128 v[220:223], v244 offset:16384
	ds_read_b128 v[224:227], v244 offset:16640
	ds_read_b128 v[228:231], v244 offset:24576
	ds_read_b128 v[232:235], v244 offset:24832
	s_waitcnt lgkmcnt(0)
	v_lshlrev_b32_e32 v236, 16, v204
	v_and_b32_e32 v237, 0xffff0000, v204
	v_lshlrev_b32_e32 v238, 16, v205
	v_and_b32_e32 v239, 0xffff0000, v205
	v_lshlrev_b32_e32 v240, 16, v206
	v_and_b32_e32 v241, 0xffff0000, v206
	v_lshlrev_b32_e32 v242, 16, v207
	v_and_b32_e32 v243, 0xffff0000, v207
	v_pk_fma_f32 v[60:61], v[60:61], 0.5, v[236:237] op_sel_hi:[1,0,1]
	v_pk_fma_f32 v[62:63], v[62:63], 0.5, v[238:239] op_sel_hi:[1,0,1]
	v_pk_fma_f32 v[56:57], v[56:57], 0.5, v[240:241] op_sel_hi:[1,0,1]
	v_pk_fma_f32 v[58:59], v[58:59], 0.5, v[242:243] op_sel_hi:[1,0,1]
	v_pk_mul_f32 v[166:167], v[60:61], v[60:61]
	v_pk_fma_f32 v[166:167], v[62:63], v[62:63], v[166:167]
	v_pk_fma_f32 v[166:167], v[56:57], v[56:57], v[166:167]
	v_pk_fma_f32 v[166:167], v[58:59], v[58:59], v[166:167]
	v_cvt_pk_bf16_f32 v204, v60, v61
	v_cvt_pk_bf16_f32 v205, v62, v63
	v_cvt_pk_bf16_f32 v206, v56, v57
	v_cvt_pk_bf16_f32 v207, v58, v59
	global_store_dwordx4 v[156:157], v[204:207], off
	v_lshlrev_b32_e32 v236, 16, v208
	v_and_b32_e32 v237, 0xffff0000, v208
	v_lshlrev_b32_e32 v238, 16, v209
	v_and_b32_e32 v239, 0xffff0000, v209
	v_lshlrev_b32_e32 v240, 16, v210
	v_and_b32_e32 v241, 0xffff0000, v210
	v_lshlrev_b32_e32 v242, 16, v211
	v_and_b32_e32 v243, 0xffff0000, v211
	v_pk_fma_f32 v[44:45], v[44:45], 0.5, v[236:237] op_sel_hi:[1,0,1]
	v_pk_fma_f32 v[46:47], v[46:47], 0.5, v[238:239] op_sel_hi:[1,0,1]
	v_pk_fma_f32 v[36:37], v[36:37], 0.5, v[240:241] op_sel_hi:[1,0,1]
	v_pk_fma_f32 v[38:39], v[38:39], 0.5, v[242:243] op_sel_hi:[1,0,1]
	v_pk_fma_f32 v[166:167], v[44:45], v[44:45], v[166:167]
	v_pk_fma_f32 v[166:167], v[46:47], v[46:47], v[166:167]
	v_pk_fma_f32 v[166:167], v[36:37], v[36:37], v[166:167]
	v_pk_fma_f32 v[166:167], v[38:39], v[38:39], v[166:167]
	v_cvt_pk_bf16_f32 v208, v44, v45
	v_cvt_pk_bf16_f32 v209, v46, v47
	v_cvt_pk_bf16_f32 v210, v36, v37
	v_cvt_pk_bf16_f32 v211, v38, v39
	global_store_dwordx4 v[156:157], v[208:211], off offset:256
	s_nop 0
	v_add_f32_e32 v156, v166, v167
	v_lshlrev_b32_e32 v236, 16, v212
	v_and_b32_e32 v237, 0xffff0000, v212
	v_lshlrev_b32_e32 v238, 16, v213
	v_and_b32_e32 v239, 0xffff0000, v213
	v_lshlrev_b32_e32 v240, 16, v214
	v_and_b32_e32 v241, 0xffff0000, v214
	v_lshlrev_b32_e32 v242, 16, v215
	v_and_b32_e32 v243, 0xffff0000, v215
	v_pk_fma_f32 v[52:53], v[52:53], 0.5, v[236:237] op_sel_hi:[1,0,1]
	v_pk_fma_f32 v[54:55], v[54:55], 0.5, v[238:239] op_sel_hi:[1,0,1]
	v_pk_fma_f32 v[48:49], v[48:49], 0.5, v[240:241] op_sel_hi:[1,0,1]
	v_pk_fma_f32 v[50:51], v[50:51], 0.5, v[242:243] op_sel_hi:[1,0,1]
	v_pk_mul_f32 v[166:167], v[52:53], v[52:53]
	v_pk_fma_f32 v[166:167], v[54:55], v[54:55], v[166:167]
	v_pk_fma_f32 v[166:167], v[48:49], v[48:49], v[166:167]
	v_pk_fma_f32 v[166:167], v[50:51], v[50:51], v[166:167]
	v_cvt_pk_bf16_f32 v212, v52, v53
	v_cvt_pk_bf16_f32 v213, v54, v55
	v_cvt_pk_bf16_f32 v214, v48, v49
	v_cvt_pk_bf16_f32 v215, v50, v51
	global_store_dwordx4 v[160:161], v[212:215], off
	v_lshlrev_b32_e32 v236, 16, v216
	v_and_b32_e32 v237, 0xffff0000, v216
	v_lshlrev_b32_e32 v238, 16, v217
	v_and_b32_e32 v239, 0xffff0000, v217
	v_lshlrev_b32_e32 v240, 16, v218
	v_and_b32_e32 v241, 0xffff0000, v218
	v_lshlrev_b32_e32 v242, 16, v219
	v_and_b32_e32 v243, 0xffff0000, v219
	v_pk_fma_f32 v[28:29], v[28:29], 0.5, v[236:237] op_sel_hi:[1,0,1]
	v_pk_fma_f32 v[30:31], v[30:31], 0.5, v[238:239] op_sel_hi:[1,0,1]
	v_pk_fma_f32 v[20:21], v[20:21], 0.5, v[240:241] op_sel_hi:[1,0,1]
	v_pk_fma_f32 v[22:23], v[22:23], 0.5, v[242:243] op_sel_hi:[1,0,1]
	v_pk_fma_f32 v[166:167], v[28:29], v[28:29], v[166:167]
	v_pk_fma_f32 v[166:167], v[30:31], v[30:31], v[166:167]
	v_pk_fma_f32 v[166:167], v[20:21], v[20:21], v[166:167]
	v_pk_fma_f32 v[166:167], v[22:23], v[22:23], v[166:167]
	v_cvt_pk_bf16_f32 v216, v28, v29
	v_cvt_pk_bf16_f32 v217, v30, v31
	v_cvt_pk_bf16_f32 v218, v20, v21
	v_cvt_pk_bf16_f32 v219, v22, v23
	global_store_dwordx4 v[160:161], v[216:219], off offset:256
	s_nop 0
	v_add_f32_e32 v160, v166, v167
	v_lshlrev_b32_e32 v236, 16, v220
	v_and_b32_e32 v237, 0xffff0000, v220
	v_lshlrev_b32_e32 v238, 16, v221
	v_and_b32_e32 v239, 0xffff0000, v221
	v_lshlrev_b32_e32 v240, 16, v222
	v_and_b32_e32 v241, 0xffff0000, v222
	v_lshlrev_b32_e32 v242, 16, v223
	v_and_b32_e32 v243, 0xffff0000, v223
	v_pk_fma_f32 v[40:41], v[40:41], 0.5, v[236:237] op_sel_hi:[1,0,1]
	v_pk_fma_f32 v[42:43], v[42:43], 0.5, v[238:239] op_sel_hi:[1,0,1]
	v_pk_fma_f32 v[32:33], v[32:33], 0.5, v[240:241] op_sel_hi:[1,0,1]
	v_pk_fma_f32 v[34:35], v[34:35], 0.5, v[242:243] op_sel_hi:[1,0,1]
	v_pk_mul_f32 v[166:167], v[40:41], v[40:41]
	v_pk_fma_f32 v[166:167], v[42:43], v[42:43], v[166:167]
	v_pk_fma_f32 v[166:167], v[32:33], v[32:33], v[166:167]
	v_pk_fma_f32 v[166:167], v[34:35], v[34:35], v[166:167]
	v_cvt_pk_bf16_f32 v220, v40, v41
	v_cvt_pk_bf16_f32 v221, v42, v43
	v_cvt_pk_bf16_f32 v222, v32, v33
; #define PG8_BAR __builtin_amdgcn_s_barrier()
;     __device__ __forceinline__ void operator()(const f32x4 (&acc)[2][2][4][2], const Unit& u, int wr, int wc, int fr, int fq) const {
;     ...
;                 ss += __shfl_xor(ss, 16); ss += __shfl_xor(ss, 32);
;                 if (fq == 0) SS[(size_t)r * 16 + u.pn * 4 + wc] = ss;
; template <class Epi, class Sched, bool ALIGN_EPI = false, bool SP2 = false>
; __device__ __forceinline__ void gemm_phase(PG8_LAS unsigned char* lds, const Gemm g, const Sched& S, const Epi& E) {
;     ...
;         if (!has_next) break;
; #pragma unroll
;         for (int a = 0; a < 2; ++a)
; #pragma unroll
;             for (int b = 0; b < 2; ++b)
; #pragma unroll
;                 for (int m = 0; m < 4; ++m)
; #pragma unroll
;                     for (int n = 0; n < 2; ++n) acc[a][b][m][n] = (f32x4){0.f, 0.f, 0.f, 0.f};
;         cur = nxt; cA = nA; cB = nB; ++ui;
;         if constexpr (ALIGN_EPI) { if (wr == 1) PG8_BAR; }
	v_cvt_pk_bf16_f32 v223, v34, v35
	global_store_dwordx4 v[162:163], v[220:223], off
	v_lshlrev_b32_e32 v236, 16, v224
	v_and_b32_e32 v237, 0xffff0000, v224
	v_lshlrev_b32_e32 v238, 16, v225
	v_and_b32_e32 v239, 0xffff0000, v225
	v_lshlrev_b32_e32 v240, 16, v226
	v_and_b32_e32 v241, 0xffff0000, v226
	v_lshlrev_b32_e32 v242, 16, v227
	v_and_b32_e32 v243, 0xffff0000, v227
	v_pk_fma_f32 v[12:13], v[12:13], 0.5, v[236:237] op_sel_hi:[1,0,1]
	v_pk_fma_f32 v[14:15], v[14:15], 0.5, v[238:239] op_sel_hi:[1,0,1]
	v_pk_fma_f32 v[8:9], v[8:9], 0.5, v[240:241] op_sel_hi:[1,0,1]
	v_pk_fma_f32 v[10:11], v[10:11], 0.5, v[242:243] op_sel_hi:[1,0,1]
	v_pk_fma_f32 v[166:167], v[12:13], v[12:13], v[166:167]
	v_pk_fma_f32 v[166:167], v[14:15], v[14:15], v[166:167]
	v_pk_fma_f32 v[166:167], v[8:9], v[8:9], v[166:167]
	v_pk_fma_f32 v[166:167], v[10:11], v[10:11], v[166:167]
	v_cvt_pk_bf16_f32 v224, v12, v13
	v_cvt_pk_bf16_f32 v225, v14, v15
	v_cvt_pk_bf16_f32 v226, v8, v9
	v_cvt_pk_bf16_f32 v227, v10, v11
	global_store_dwordx4 v[162:163], v[224:227], off offset:256
	s_nop 0
	v_add_f32_e32 v162, v166, v167
	v_lshlrev_b32_e32 v236, 16, v228
	v_and_b32_e32 v237, 0xffff0000, v228
	v_lshlrev_b32_e32 v238, 16, v229
	v_and_b32_e32 v239, 0xffff0000, v229
	v_lshlrev_b32_e32 v240, 16, v230
	v_and_b32_e32 v241, 0xffff0000, v230
	v_lshlrev_b32_e32 v242, 16, v231
	v_and_b32_e32 v243, 0xffff0000, v231
	v_pk_fma_f32 v[24:25], v[24:25], 0.5, v[236:237] op_sel_hi:[1,0,1]
	v_pk_fma_f32 v[26:27], v[26:27], 0.5, v[238:239] op_sel_hi:[1,0,1]
	v_pk_fma_f32 v[16:17], v[16:17], 0.5, v[240:241] op_sel_hi:[1,0,1]
	v_pk_fma_f32 v[18:19], v[18:19], 0.5, v[242:243] op_sel_hi:[1,0,1]
	v_pk_mul_f32 v[166:167], v[24:25], v[24:25]
	v_pk_fma_f32 v[166:167], v[26:27], v[26:27], v[166:167]
	v_pk_fma_f32 v[166:167], v[16:17], v[16:17], v[166:167]
	v_pk_fma_f32 v[166:167], v[18:19], v[18:19], v[166:167]
	v_cvt_pk_bf16_f32 v228, v24, v25
	v_cvt_pk_bf16_f32 v229, v26, v27
	v_cvt_pk_bf16_f32 v230, v16, v17
	v_cvt_pk_bf16_f32 v231, v18, v19
	global_store_dwordx4 v[164:165], v[228:231], off
	v_lshlrev_b32_e32 v236, 16, v232
	v_and_b32_e32 v237, 0xffff0000, v232
	v_lshlrev_b32_e32 v238, 16, v233
	v_and_b32_e32 v239, 0xffff0000, v233
	v_lshlrev_b32_e32 v240, 16, v234
	v_and_b32_e32 v241, 0xffff0000, v234
	v_lshlrev_b32_e32 v242, 16, v235
	v_and_b32_e32 v243, 0xffff0000, v235
	v_pk_fma_f32 v[4:5], v[4:5], 0.5, v[236:237] op_sel_hi:[1,0,1]
	v_pk_fma_f32 v[6:7], v[6:7], 0.5, v[238:239] op_sel_hi:[1,0,1]
	v_pk_fma_f32 v[0:1], v[0:1], 0.5, v[240:241] op_sel_hi:[1,0,1]
	v_pk_fma_f32 v[2:3], v[2:3], 0.5, v[242:243] op_sel_hi:[1,0,1]
	v_pk_fma_f32 v[166:167], v[4:5], v[4:5], v[166:167]
	v_pk_fma_f32 v[166:167], v[6:7], v[6:7], v[166:167]
	v_pk_fma_f32 v[166:167], v[0:1], v[0:1], v[166:167]
	v_pk_fma_f32 v[166:167], v[2:3], v[2:3], v[166:167]
	v_cvt_pk_bf16_f32 v232, v4, v5
	v_cvt_pk_bf16_f32 v233, v6, v7
	v_cvt_pk_bf16_f32 v234, v0, v1
	v_cvt_pk_bf16_f32 v235, v2, v3
	global_store_dwordx4 v[164:165], v[232:235], off offset:256
	s_nop 0
	v_add_f32_e32 v164, v166, v167
	ds_bpermute_b32 v149, v128, v148
	ds_bpermute_b32 v151, v128, v150
	ds_bpermute_b32 v153, v128, v152
	ds_bpermute_b32 v155, v128, v154
	ds_bpermute_b32 v157, v128, v156
	ds_bpermute_b32 v161, v128, v160
	ds_bpermute_b32 v163, v128, v162
	ds_bpermute_b32 v165, v128, v164
	s_waitcnt lgkmcnt(7)
	v_add_f32_e32 v148, v148, v149
	s_waitcnt lgkmcnt(6)
	v_add_f32_e32 v150, v150, v151
	s_waitcnt lgkmcnt(5)
	v_add_f32_e32 v152, v152, v153
	s_waitcnt lgkmcnt(4)
	v_add_f32_e32 v154, v154, v155
	s_waitcnt lgkmcnt(3)
	v_add_f32_e32 v156, v156, v157
	s_waitcnt lgkmcnt(2)
	v_add_f32_e32 v160, v160, v161
	s_waitcnt lgkmcnt(1)
	v_add_f32_e32 v162, v162, v163
	s_waitcnt lgkmcnt(0)
	v_add_f32_e32 v164, v164, v165
	ds_bpermute_b32 v149, v158, v148
	ds_bpermute_b32 v151, v158, v150
	ds_bpermute_b32 v153, v158, v152
	ds_bpermute_b32 v155, v158, v154
	ds_bpermute_b32 v157, v158, v156
	ds_bpermute_b32 v161, v158, v160
	ds_bpermute_b32 v163, v158, v162
	ds_bpermute_b32 v165, v158, v164
	s_waitcnt lgkmcnt(7)
	v_add_f32_e32 v148, v148, v149
	s_waitcnt lgkmcnt(6)
	v_add_f32_e32 v150, v150, v151
	s_waitcnt lgkmcnt(5)
	v_add_f32_e32 v152, v152, v153
	s_waitcnt lgkmcnt(4)
	v_add_f32_e32 v154, v154, v155
	s_waitcnt lgkmcnt(3)
	v_add_f32_e32 v156, v156, v157
	s_waitcnt lgkmcnt(2)
	v_add_f32_e32 v160, v160, v161
	s_waitcnt lgkmcnt(1)
	v_add_f32_e32 v162, v162, v163
	s_waitcnt lgkmcnt(0)
	v_add_f32_e32 v164, v164, v165
	s_and_saveexec_b64 s[88:89], s[6:7]
	global_store_dword v[194:195], v148, off
	global_store_dword v[194:195], v150, off offset:1024
	global_store_dword v[194:195], v152, off offset:2048
	global_store_dword v[194:195], v154, off offset:3072
	s_movk_i32 s84, 0x2000
	v_lshl_add_u64 v[194:195], v[194:195], 0, s[84:85]
	global_store_dword v[194:195], v156, off
	global_store_dword v[194:195], v160, off offset:1024
	global_store_dword v[194:195], v162, off offset:2048
	global_store_dword v[194:195], v164, off offset:3072
	s_or_b64 exec, exec, s[88:89]
	v_and_b32_e32 v56, 64, v247
	v_add_u32_e32 v56, 64, v56
	s_and_b64 vcc, exec, s[8:9]
	s_mov_b64 s[8:9], -1
	s_cbranch_vccnz .LBB0_355
	s_andn2_b64 vcc, exec, s[22:23]
	s_cbranch_vccnz .LBB0_354
	s_barrier
	s_branch .LBB0_354

; __device__ __forceinline__ unsigned cvt_pk_bf16(float lo, float hi) { unsigned r; asm volatile("v_cvt_pk_bf16_f32 %0, %1, %2" : "=v"(r) : "v"(lo), "v"(hi)); return r; }
; __device__ __forceinline__ unsigned cvt_pk_bf16(float lo, float hi) { const f32x2 v = {lo, hi}; const bf16x2_t b = __builtin_convertvector(v, bf16x2_t); return __builtin_bit_cast(unsigned, b); }
;     __device__ __forceinline__ void operator()(const f32x4 (&acc)[2][2][4][2], const Unit& u, int wr, int wc, int fr, int fq) const {
;         const int row0 = u.pm * BM + wr * 64 + fr, col0 = u.pn * BM + wc * 32 + 8 * fq;
;         u32x4 rb[2][4][2];
; #pragma unroll
;         for (int ai = 0; ai < 2; ++ai)
; #pragma unroll
;             for (int m = 0; m < 4; ++m) { const bf16_t* xq = XB + (size_t)(row0 + ai * HALF + m * 16) * 1024 + col0; rb[ai][m][0] = *(const u32x4*)xq; rb[ai][m][1] = *(const u32x4*)(xq + HALF); }
; #pragma unroll
;         for (int ai = 0; ai < 2; ++ai) {
; #pragma unroll
;             for (int m = 0; m < 4; ++m) {
;                 const int r = row0 + ai * HALF + m * 16;
;                 bf16_t* xp = XB + (size_t)r * 1024 + col0;
;                 const u32x4 b0 = rb[ai][m][0], b1 = rb[ai][m][1];
;                 float ss = 0.f;
; #pragma unroll
;                 for (int bj = 0; bj < 2; ++bj) {
;                     const u32x4 b = bj ? b1 : b0;
;                     f32x4 v0, v1;
;                     v0[0] = __uint_as_float(b.x << 16); v0[1] = __uint_as_float(b.x & 0xffff0000u); v0[2] = __uint_as_float(b.y << 16); v0[3] = __uint_as_float(b.y & 0xffff0000u);
;                     v1[0] = __uint_as_float(b.z << 16); v1[1] = __uint_as_float(b.z & 0xffff0000u); v1[2] = __uint_as_float(b.w << 16); v1[3] = __uint_as_float(b.w & 0xffff0000u);
;                     v0 += acc[ai][bj][m][0] * alpha; v1 += acc[ai][bj][m][1] * alpha;
;                     ss += (v0[0] * v0[0] + v0[1] * v0[1]) + (v0[2] * v0[2] + v0[3] * v0[3]) + (v1[0] * v1[0] + v1[1] * v1[1]) + (v1[2] * v1[2] + v1[3] * v1[3]);
;                     u32x4 w; w.x = cvt_pk_bf16(v0[0], v0[1]); w.y = cvt_pk_bf16(v0[2], v0[3]); w.z = cvt_pk_bf16(v1[0], v1[1]); w.w = cvt_pk_bf16(v1[2], v1[3]);
;                     *(u32x4*)(xp + bj * HALF) = w;
;                 }
.LBB0_924:
	v_lshl_or_b32 v128, s18, 8, v245
	v_lshl_add_u32 v130, s4, 8, v193
	v_lshlrev_b32_e32 v128, 1, v128
	v_mov_b32_e32 v129, 0
	v_mov_b32_e32 v131, 0
	s_mov_b32 s84, 0x8000
	s_mov_b32 s85, 0
	s_mov_b32 s86, 0x40000
	s_mov_b32 s87, 0
	v_lshl_add_u64 v[132:133], s[34:35], 0, v[128:129]
	v_lshlrev_b32_e32 v228, 11, v130
	v_mov_b32_e32 v229, 0
	v_lshl_add_u64 v[132:133], v[132:133], 0, v[228:229]
	v_lshl_add_u64 v[140:141], v[132:133], 0, s[86:87]
	v_lshl_add_u64 v[134:135], v[132:133], 0, s[84:85]
	v_lshl_add_u64 v[136:137], v[134:135], 0, s[84:85]
	v_lshl_add_u64 v[138:139], v[136:137], 0, s[84:85]
	v_lshl_add_u64 v[142:143], v[140:141], 0, s[84:85]
	v_lshl_add_u64 v[144:145], v[142:143], 0, s[84:85]
	v_lshl_add_u64 v[146:147], v[144:145], 0, s[84:85]
	v_readfirstlane_b32 s101, v192
	s_nop 1
	s_lshr_b32 s101, s101, 6
	v_lshrrev_b32_e32 v232, 5, v246
	v_and_b32_e32 v233, 31, v246
	v_mov_b32_e32 v234, v232
	v_xor_b32_e32 v235, v233, v234
	v_lshlrev_b32_e32 v235, 4, v235
	v_lshl_add_u32 v152, v234, 11, v235
	v_or_b32_e32 v234, 2, v232
	v_xor_b32_e32 v235, v233, v234
	v_lshlrev_b32_e32 v235, 4, v235
	v_lshl_add_u32 v160, v234, 11, v235
	v_or_b32_e32 v234, 4, v232
	v_xor_b32_e32 v235, v233, v234
	v_lshlrev_b32_e32 v235, 4, v235
	v_lshl_add_u32 v168, v234, 11, v235
	v_or_b32_e32 v234, 6, v232
	v_xor_b32_e32 v235, v233, v234
	v_lshlrev_b32_e32 v235, 4, v235
	v_lshl_add_u32 v176, v234, 11, v235
	v_or_b32_e32 v234, 8, v232
	v_xor_b32_e32 v235, v233, v234
	v_lshlrev_b32_e32 v235, 4, v235
	v_lshl_add_u32 v184, v234, 11, v235
	v_or_b32_e32 v234, 10, v232
	v_xor_b32_e32 v235, v233, v234
	v_lshlrev_b32_e32 v235, 4, v235
	v_lshl_add_u32 v208, v234, 11, v235
	v_or_b32_e32 v234, 12, v232
	v_xor_b32_e32 v235, v233, v234
	v_lshlrev_b32_e32 v235, 4, v235
	v_lshl_add_u32 v216, v234, 11, v235
	v_or_b32_e32 v234, 14, v232
	v_xor_b32_e32 v235, v233, v234
	v_lshlrev_b32_e32 v235, 4, v235
	v_lshl_add_u32 v224, v234, 11, v235
	s_lshl_b32 s98, s4, 19
	s_lshl_b32 s99, s101, 15
	s_add_u32 s98, s98, s99
	s_lshl_b32 s99, s18, 9
	s_add_u32 s98, s98, s99
	s_add_u32 s98, s34, s98
	s_addc_u32 s99, s35, 0
	s_lshl_b32 s100, s101, 13
	s_waitcnt vmcnt(0)
	s_barrier
	s_add_i32 m0, s100, 0x0
	s_nop 0
	global_load_lds_dwordx4 v152, s[98:99]
	s_add_i32 m0, s100, 0x400
	s_nop 0
	global_load_lds_dwordx4 v160, s[98:99]
	s_add_i32 m0, s100, 0x800
	s_nop 0
	global_load_lds_dwordx4 v168, s[98:99]
	s_add_i32 m0, s100, 0xc00
	s_nop 0
	global_load_lds_dwordx4 v176, s[98:99]
	s_add_i32 m0, s100, 0x1000
	s_nop 0
	global_load_lds_dwordx4 v184, s[98:99]
	s_add_i32 m0, s100, 0x1400
	s_nop 0
	global_load_lds_dwordx4 v208, s[98:99]
	s_add_i32 m0, s100, 0x1800
	s_nop 0
	global_load_lds_dwordx4 v216, s[98:99]
	s_add_i32 m0, s100, 0x1c00
	s_nop 0
	global_load_lds_dwordx4 v224, s[98:99]
	s_add_u32 s98, s98, 0x40000
	s_addc_u32 s99, s99, 0
	s_add_i32 m0, s100, 0x10000
	s_nop 0
	global_load_lds_dwordx4 v152, s[98:99]
	s_add_i32 m0, s100, 0x10400
	s_nop 0
	global_load_lds_dwordx4 v160, s[98:99]
	s_add_i32 m0, s100, 0x10800
	s_nop 0
	global_load_lds_dwordx4 v168, s[98:99]
	s_add_i32 m0, s100, 0x10c00
	s_nop 0
	global_load_lds_dwordx4 v176, s[98:99]
	s_add_i32 m0, s100, 0x11000
	s_nop 0
	global_load_lds_dwordx4 v184, s[98:99]
	s_add_i32 m0, s100, 0x11400
	s_nop 0
	global_load_lds_dwordx4 v208, s[98:99]
	s_add_i32 m0, s100, 0x11800
	s_nop 0
	global_load_lds_dwordx4 v216, s[98:99]
	s_add_i32 m0, s100, 0x11c00
	s_nop 0
	global_load_lds_dwordx4 v224, s[98:99]
	v_lshrrev_b32_e32 v230, 3, v245
	v_and_b32_e32 v231, 15, v193
	v_xor_b32_e32 v230, v230, v231
	v_lshlrev_b32_e32 v230, 4, v230
	v_lshl_add_u32 v228, v193, 9, v230
	v_add_u32_e32 v242, 0x10000, v228
	s_waitcnt vmcnt(8)
	s_barrier
	ds_read_b128 v[148:151], v228
	ds_read_b128 v[152:155], v228 offset:256
	ds_read_b128 v[156:159], v228 offset:8192
	ds_read_b128 v[160:163], v228 offset:8448
	ds_read_b128 v[164:167], v228 offset:16384
	ds_read_b128 v[168:171], v228 offset:16640
	ds_read_b128 v[172:175], v228 offset:24576
	ds_read_b128 v[176:179], v228 offset:24832
	s_waitcnt lgkmcnt(0)
	v_xor_b32_e32 v238, 16, v246
	v_xor_b32_e32 v239, 32, v246
	v_lshlrev_b32_e32 v238, 2, v238
	v_lshlrev_b32_e32 v239, 2, v239
	s_lshl_b32 s90, s18, 2
	s_add_i32 s90, s90, s64
	s_lshl_b32 s90, s90, 2
	s_mov_b32 s91, 0
	v_lshlrev_b32_e32 v230, 6, v130
	v_mov_b32_e32 v231, 0
	v_lshl_add_u64 v[240:241], s[44:45], 0, v[230:231]
	v_lshl_add_u64 v[240:241], v[240:241], 0, s[90:91]
	v_lshlrev_b32_e32 v228, 16, v148
	v_and_b32_e32 v229, 0xffff0000, v148
	v_lshlrev_b32_e32 v230, 16, v149
	v_and_b32_e32 v231, 0xffff0000, v149
	v_lshlrev_b32_e32 v232, 16, v150
	v_and_b32_e32 v233, 0xffff0000, v150
	v_lshlrev_b32_e32 v234, 16, v151
	v_and_b32_e32 v235, 0xffff0000, v151
	v_pk_add_f32 v[120:121], v[120:121], v[228:229]
	v_pk_add_f32 v[122:123], v[122:123], v[230:231]
	v_pk_add_f32 v[124:125], v[124:125], v[232:233]
	v_pk_add_f32 v[126:127], v[126:127], v[234:235]
	v_pk_mul_f32 v[236:237], v[120:121], v[120:121]
	v_pk_fma_f32 v[236:237], v[122:123], v[122:123], v[236:237]
	v_pk_fma_f32 v[236:237], v[124:125], v[124:125], v[236:237]
	v_pk_fma_f32 v[236:237], v[126:127], v[126:127], v[236:237]
	v_cvt_pk_bf16_f32 v148, v120, v121
	v_cvt_pk_bf16_f32 v149, v122, v123
	v_cvt_pk_bf16_f32 v150, v124, v125
	v_cvt_pk_bf16_f32 v151, v126, v127
	global_store_dwordx4 v[132:133], v[148:151], off
	v_lshlrev_b32_e32 v228, 16, v152
	v_and_b32_e32 v229, 0xffff0000, v152
	v_lshlrev_b32_e32 v230, 16, v153
	v_and_b32_e32 v231, 0xffff0000, v153
	v_lshlrev_b32_e32 v232, 16, v154
	v_and_b32_e32 v233, 0xffff0000, v154
	v_lshlrev_b32_e32 v234, 16, v155
	v_and_b32_e32 v235, 0xffff0000, v155
; __device__ __forceinline__ unsigned cvt_pk_bf16(float lo, float hi) { unsigned r; asm volatile("v_cvt_pk_bf16_f32 %0, %1, %2" : "=v"(r) : "v"(lo), "v"(hi)); return r; }
; __device__ __forceinline__ unsigned cvt_pk_bf16(float lo, float hi) { const f32x2 v = {lo, hi}; const bf16x2_t b = __builtin_convertvector(v, bf16x2_t); return __builtin_bit_cast(unsigned, b); }
;     __device__ __forceinline__ void operator()(const f32x4 (&acc)[2][2][4][2], const Unit& u, int wr, int wc, int fr, int fq) const {
;     ...
;                 const int r = row0 + ai * HALF + m * 16;
;                 bf16_t* xp = XB + (size_t)r * 1024 + col0;
;                 const u32x4 b0 = rb[ai][m][0], b1 = rb[ai][m][1];
;                 float ss = 0.f;
; #pragma unroll
;                 for (int bj = 0; bj < 2; ++bj) {
;                     const u32x4 b = bj ? b1 : b0;
;                     f32x4 v0, v1;
;                     v0[0] = __uint_as_float(b.x << 16); v0[1] = __uint_as_float(b.x & 0xffff0000u); v0[2] = __uint_as_float(b.y << 16); v0[3] = __uint_as_float(b.y & 0xffff0000u);
;                     v1[0] = __uint_as_float(b.z << 16); v1[1] = __uint_as_float(b.z & 0xffff0000u); v1[2] = __uint_as_float(b.w << 16); v1[3] = __uint_as_float(b.w & 0xffff0000u);
;                     v0 += acc[ai][bj][m][0] * alpha; v1 += acc[ai][bj][m][1] * alpha;
;                     ss += (v0[0] * v0[0] + v0[1] * v0[1]) + (v0[2] * v0[2] + v0[3] * v0[3]) + (v1[0] * v1[0] + v1[1] * v1[1]) + (v1[2] * v1[2] + v1[3] * v1[3]);
;                     u32x4 w; w.x = cvt_pk_bf16(v0[0], v0[1]); w.y = cvt_pk_bf16(v0[2], v0[3]); w.z = cvt_pk_bf16(v1[0], v1[1]); w.w = cvt_pk_bf16(v1[2], v1[3]);
;                     *(u32x4*)(xp + bj * HALF) = w;
;                 }
	v_pk_add_f32 v[116:117], v[116:117], v[228:229]
	v_pk_add_f32 v[118:119], v[118:119], v[230:231]
	v_pk_add_f32 v[112:113], v[112:113], v[232:233]
	v_pk_add_f32 v[114:115], v[114:115], v[234:235]
	v_pk_fma_f32 v[236:237], v[116:117], v[116:117], v[236:237]
	v_pk_fma_f32 v[236:237], v[118:119], v[118:119], v[236:237]
	v_pk_fma_f32 v[236:237], v[112:113], v[112:113], v[236:237]
	v_pk_fma_f32 v[236:237], v[114:115], v[114:115], v[236:237]
	v_cvt_pk_bf16_f32 v152, v116, v117
	v_cvt_pk_bf16_f32 v153, v118, v119
	v_cvt_pk_bf16_f32 v154, v112, v113
	v_cvt_pk_bf16_f32 v155, v114, v115
	global_store_dwordx4 v[132:133], v[152:155], off offset:256
	s_nop 0
	v_add_f32_e32 v132, v236, v237
	v_lshlrev_b32_e32 v228, 16, v156
	v_and_b32_e32 v229, 0xffff0000, v156
	v_lshlrev_b32_e32 v230, 16, v157
	v_and_b32_e32 v231, 0xffff0000, v157
	v_lshlrev_b32_e32 v232, 16, v158
	v_and_b32_e32 v233, 0xffff0000, v158
	v_lshlrev_b32_e32 v234, 16, v159
	v_and_b32_e32 v235, 0xffff0000, v159
	v_pk_add_f32 v[108:109], v[108:109], v[228:229]
	v_pk_add_f32 v[110:111], v[110:111], v[230:231]
	v_pk_add_f32 v[104:105], v[104:105], v[232:233]
	v_pk_add_f32 v[106:107], v[106:107], v[234:235]
	v_pk_mul_f32 v[236:237], v[108:109], v[108:109]
	v_pk_fma_f32 v[236:237], v[110:111], v[110:111], v[236:237]
	v_pk_fma_f32 v[236:237], v[104:105], v[104:105], v[236:237]
	v_pk_fma_f32 v[236:237], v[106:107], v[106:107], v[236:237]
	v_cvt_pk_bf16_f32 v156, v108, v109
	v_cvt_pk_bf16_f32 v157, v110, v111
	v_cvt_pk_bf16_f32 v158, v104, v105
	v_cvt_pk_bf16_f32 v159, v106, v107
	global_store_dwordx4 v[134:135], v[156:159], off
	v_lshlrev_b32_e32 v228, 16, v160
	v_and_b32_e32 v229, 0xffff0000, v160
	v_lshlrev_b32_e32 v230, 16, v161
	v_and_b32_e32 v231, 0xffff0000, v161
	v_lshlrev_b32_e32 v232, 16, v162
	v_and_b32_e32 v233, 0xffff0000, v162
	v_lshlrev_b32_e32 v234, 16, v163
	v_and_b32_e32 v235, 0xffff0000, v163
	v_pk_add_f32 v[100:101], v[100:101], v[228:229]
	v_pk_add_f32 v[102:103], v[102:103], v[230:231]
	v_pk_add_f32 v[96:97], v[96:97], v[232:233]
	v_pk_add_f32 v[98:99], v[98:99], v[234:235]
	v_pk_fma_f32 v[236:237], v[100:101], v[100:101], v[236:237]
	v_pk_fma_f32 v[236:237], v[102:103], v[102:103], v[236:237]
	v_pk_fma_f32 v[236:237], v[96:97], v[96:97], v[236:237]
	v_pk_fma_f32 v[236:237], v[98:99], v[98:99], v[236:237]
	v_cvt_pk_bf16_f32 v160, v100, v101
	v_cvt_pk_bf16_f32 v161, v102, v103
	v_cvt_pk_bf16_f32 v162, v96, v97
	v_cvt_pk_bf16_f32 v163, v98, v99
	global_store_dwordx4 v[134:135], v[160:163], off offset:256
	s_nop 0
	v_add_f32_e32 v134, v236, v237
	v_lshlrev_b32_e32 v228, 16, v164
	v_and_b32_e32 v229, 0xffff0000, v164
	v_lshlrev_b32_e32 v230, 16, v165
	v_and_b32_e32 v231, 0xffff0000, v165
	v_lshlrev_b32_e32 v232, 16, v166
	v_and_b32_e32 v233, 0xffff0000, v166
	v_lshlrev_b32_e32 v234, 16, v167
	v_and_b32_e32 v235, 0xffff0000, v167
	v_pk_add_f32 v[92:93], v[92:93], v[228:229]
	v_pk_add_f32 v[94:95], v[94:95], v[230:231]
	v_pk_add_f32 v[88:89], v[88:89], v[232:233]
	v_pk_add_f32 v[90:91], v[90:91], v[234:235]
	v_pk_mul_f32 v[236:237], v[92:93], v[92:93]
	v_pk_fma_f32 v[236:237], v[94:95], v[94:95], v[236:237]
	v_pk_fma_f32 v[236:237], v[88:89], v[88:89], v[236:237]
	v_pk_fma_f32 v[236:237], v[90:91], v[90:91], v[236:237]
	v_cvt_pk_bf16_f32 v164, v92, v93
	v_cvt_pk_bf16_f32 v165, v94, v95
	v_cvt_pk_bf16_f32 v166, v88, v89
	v_cvt_pk_bf16_f32 v167, v90, v91
	global_store_dwordx4 v[136:137], v[164:167], off
	v_lshlrev_b32_e32 v228, 16, v168
	v_and_b32_e32 v229, 0xffff0000, v168
	v_lshlrev_b32_e32 v230, 16, v169
	v_and_b32_e32 v231, 0xffff0000, v169
	v_lshlrev_b32_e32 v232, 16, v170
	v_and_b32_e32 v233, 0xffff0000, v170
	v_lshlrev_b32_e32 v234, 16, v171
	v_and_b32_e32 v235, 0xffff0000, v171
	v_pk_add_f32 v[84:85], v[84:85], v[228:229]
	v_pk_add_f32 v[86:87], v[86:87], v[230:231]
	v_pk_add_f32 v[80:81], v[80:81], v[232:233]
	v_pk_add_f32 v[82:83], v[82:83], v[234:235]
	v_pk_fma_f32 v[236:237], v[84:85], v[84:85], v[236:237]
	v_pk_fma_f32 v[236:237], v[86:87], v[86:87], v[236:237]
	v_pk_fma_f32 v[236:237], v[80:81], v[80:81], v[236:237]
	v_pk_fma_f32 v[236:237], v[82:83], v[82:83], v[236:237]
	v_cvt_pk_bf16_f32 v168, v84, v85
	v_cvt_pk_bf16_f32 v169, v86, v87
	v_cvt_pk_bf16_f32 v170, v80, v81
	v_cvt_pk_bf16_f32 v171, v82, v83
	global_store_dwordx4 v[136:137], v[168:171], off offset:256
	s_nop 0
	v_add_f32_e32 v136, v236, v237
	v_lshlrev_b32_e32 v228, 16, v172
	v_and_b32_e32 v229, 0xffff0000, v172
	v_lshlrev_b32_e32 v230, 16, v173
	v_and_b32_e32 v231, 0xffff0000, v173
	v_lshlrev_b32_e32 v232, 16, v174
	v_and_b32_e32 v233, 0xffff0000, v174
	v_lshlrev_b32_e32 v234, 16, v175
	v_and_b32_e32 v235, 0xffff0000, v175
	v_pk_add_f32 v[76:77], v[76:77], v[228:229]
	v_pk_add_f32 v[78:79], v[78:79], v[230:231]
	v_pk_add_f32 v[72:73], v[72:73], v[232:233]
	v_pk_add_f32 v[74:75], v[74:75], v[234:235]
	v_pk_mul_f32 v[236:237], v[76:77], v[76:77]
	v_pk_fma_f32 v[236:237], v[78:79], v[78:79], v[236:237]
	v_pk_fma_f32 v[236:237], v[72:73], v[72:73], v[236:237]
	v_pk_fma_f32 v[236:237], v[74:75], v[74:75], v[236:237]
	v_cvt_pk_bf16_f32 v172, v76, v77
	v_cvt_pk_bf16_f32 v173, v78, v79
	v_cvt_pk_bf16_f32 v174, v72, v73
	v_cvt_pk_bf16_f32 v175, v74, v75
	global_store_dwordx4 v[138:139], v[172:175], off
	v_lshlrev_b32_e32 v228, 16, v176
	v_and_b32_e32 v229, 0xffff0000, v176
	v_lshlrev_b32_e32 v230, 16, v177
	v_and_b32_e32 v231, 0xffff0000, v177
	v_lshlrev_b32_e32 v232, 16, v178
	v_and_b32_e32 v233, 0xffff0000, v178
	v_lshlrev_b32_e32 v234, 16, v179
	v_and_b32_e32 v235, 0xffff0000, v179
	v_pk_add_f32 v[68:69], v[68:69], v[228:229]
	v_pk_add_f32 v[70:71], v[70:71], v[230:231]
	v_pk_add_f32 v[64:65], v[64:65], v[232:233]
	v_pk_add_f32 v[66:67], v[66:67], v[234:235]
	v_pk_fma_f32 v[236:237], v[68:69], v[68:69], v[236:237]
	v_pk_fma_f32 v[236:237], v[70:71], v[70:71], v[236:237]
	v_pk_fma_f32 v[236:237], v[64:65], v[64:65], v[236:237]
	v_pk_fma_f32 v[236:237], v[66:67], v[66:67], v[236:237]
	v_cvt_pk_bf16_f32 v176, v68, v69
	v_cvt_pk_bf16_f32 v177, v70, v71
	v_cvt_pk_bf16_f32 v178, v64, v65
	v_cvt_pk_bf16_f32 v179, v66, v67
	global_store_dwordx4 v[138:139], v[176:179], off offset:256
	s_nop 0
	v_add_f32_e32 v138, v236, v237
	s_waitcnt vmcnt(8)
	s_barrier
; __device__ __forceinline__ unsigned cvt_pk_bf16(float lo, float hi) { unsigned r; asm volatile("v_cvt_pk_bf16_f32 %0, %1, %2" : "=v"(r) : "v"(lo), "v"(hi)); return r; }
; __device__ __forceinline__ unsigned cvt_pk_bf16(float lo, float hi) { const f32x2 v = {lo, hi}; const bf16x2_t b = __builtin_convertvector(v, bf16x2_t); return __builtin_bit_cast(unsigned, b); }
;     __device__ __forceinline__ void operator()(const f32x4 (&acc)[2][2][4][2], const Unit& u, int wr, int wc, int fr, int fq) const {
;     ...
;                 const int r = row0 + ai * HALF + m * 16;
;                 bf16_t* xp = XB + (size_t)r * 1024 + col0;
;                 const u32x4 b0 = rb[ai][m][0], b1 = rb[ai][m][1];
;                 float ss = 0.f;
; #pragma unroll
;                 for (int bj = 0; bj < 2; ++bj) {
;                     const u32x4 b = bj ? b1 : b0;
;                     f32x4 v0, v1;
;                     v0[0] = __uint_as_float(b.x << 16); v0[1] = __uint_as_float(b.x & 0xffff0000u); v0[2] = __uint_as_float(b.y << 16); v0[3] = __uint_as_float(b.y & 0xffff0000u);
;                     v1[0] = __uint_as_float(b.z << 16); v1[1] = __uint_as_float(b.z & 0xffff0000u); v1[2] = __uint_as_float(b.w << 16); v1[3] = __uint_as_float(b.w & 0xffff0000u);
;                     v0 += acc[ai][bj][m][0] * alpha; v1 += acc[ai][bj][m][1] * alpha;
;                     ss += (v0[0] * v0[0] + v0[1] * v0[1]) + (v0[2] * v0[2] + v0[3] * v0[3]) + (v1[0] * v1[0] + v1[1] * v1[1]) + (v1[2] * v1[2] + v1[3] * v1[3]);
;                     u32x4 w; w.x = cvt_pk_bf16(v0[0], v0[1]); w.y = cvt_pk_bf16(v0[2], v0[3]); w.z = cvt_pk_bf16(v1[0], v1[1]); w.w = cvt_pk_bf16(v1[2], v1[3]);
;                     *(u32x4*)(xp + bj * HALF) = w;
;                 }
	ds_read_b128 v[180:183], v242
	ds_read_b128 v[184:187], v242 offset:256
	ds_read_b128 v[188:191], v242 offset:8192
	ds_read_b128 v[208:211], v242 offset:8448
	ds_read_b128 v[212:215], v242 offset:16384
	ds_read_b128 v[216:219], v242 offset:16640
	ds_read_b128 v[220:223], v242 offset:24576
	ds_read_b128 v[224:227], v242 offset:24832
	s_waitcnt lgkmcnt(0)
	v_lshlrev_b32_e32 v228, 16, v180
	v_and_b32_e32 v229, 0xffff0000, v180
	v_lshlrev_b32_e32 v230, 16, v181
	v_and_b32_e32 v231, 0xffff0000, v181
	v_lshlrev_b32_e32 v232, 16, v182
	v_and_b32_e32 v233, 0xffff0000, v182
	v_lshlrev_b32_e32 v234, 16, v183
	v_and_b32_e32 v235, 0xffff0000, v183
	v_pk_add_f32 v[60:61], v[60:61], v[228:229]
	v_pk_add_f32 v[62:63], v[62:63], v[230:231]
	v_pk_add_f32 v[56:57], v[56:57], v[232:233]
	v_pk_add_f32 v[58:59], v[58:59], v[234:235]
	v_pk_mul_f32 v[236:237], v[60:61], v[60:61]
	v_pk_fma_f32 v[236:237], v[62:63], v[62:63], v[236:237]
	v_pk_fma_f32 v[236:237], v[56:57], v[56:57], v[236:237]
	v_pk_fma_f32 v[236:237], v[58:59], v[58:59], v[236:237]
	v_cvt_pk_bf16_f32 v180, v60, v61
	v_cvt_pk_bf16_f32 v181, v62, v63
	v_cvt_pk_bf16_f32 v182, v56, v57
	v_cvt_pk_bf16_f32 v183, v58, v59
	global_store_dwordx4 v[140:141], v[180:183], off
	v_lshlrev_b32_e32 v228, 16, v184
	v_and_b32_e32 v229, 0xffff0000, v184
	v_lshlrev_b32_e32 v230, 16, v185
	v_and_b32_e32 v231, 0xffff0000, v185
	v_lshlrev_b32_e32 v232, 16, v186
	v_and_b32_e32 v233, 0xffff0000, v186
	v_lshlrev_b32_e32 v234, 16, v187
	v_and_b32_e32 v235, 0xffff0000, v187
	v_pk_add_f32 v[52:53], v[52:53], v[228:229]
	v_pk_add_f32 v[54:55], v[54:55], v[230:231]
	v_pk_add_f32 v[48:49], v[48:49], v[232:233]
	v_pk_add_f32 v[50:51], v[50:51], v[234:235]
	v_pk_fma_f32 v[236:237], v[52:53], v[52:53], v[236:237]
	v_pk_fma_f32 v[236:237], v[54:55], v[54:55], v[236:237]
	v_pk_fma_f32 v[236:237], v[48:49], v[48:49], v[236:237]
	v_pk_fma_f32 v[236:237], v[50:51], v[50:51], v[236:237]
	v_cvt_pk_bf16_f32 v184, v52, v53
	v_cvt_pk_bf16_f32 v185, v54, v55
	v_cvt_pk_bf16_f32 v186, v48, v49
	v_cvt_pk_bf16_f32 v187, v50, v51
	global_store_dwordx4 v[140:141], v[184:187], off offset:256
	s_nop 0
	v_add_f32_e32 v140, v236, v237
	v_lshlrev_b32_e32 v228, 16, v188
	v_and_b32_e32 v229, 0xffff0000, v188
	v_lshlrev_b32_e32 v230, 16, v189
	v_and_b32_e32 v231, 0xffff0000, v189
	v_lshlrev_b32_e32 v232, 16, v190
	v_and_b32_e32 v233, 0xffff0000, v190
	v_lshlrev_b32_e32 v234, 16, v191
	v_and_b32_e32 v235, 0xffff0000, v191
	v_pk_add_f32 v[44:45], v[44:45], v[228:229]
	v_pk_add_f32 v[46:47], v[46:47], v[230:231]
	v_pk_add_f32 v[40:41], v[40:41], v[232:233]
	v_pk_add_f32 v[42:43], v[42:43], v[234:235]
	v_pk_mul_f32 v[236:237], v[44:45], v[44:45]
	v_pk_fma_f32 v[236:237], v[46:47], v[46:47], v[236:237]
	v_pk_fma_f32 v[236:237], v[40:41], v[40:41], v[236:237]
	v_pk_fma_f32 v[236:237], v[42:43], v[42:43], v[236:237]
	v_cvt_pk_bf16_f32 v188, v44, v45
	v_cvt_pk_bf16_f32 v189, v46, v47
	v_cvt_pk_bf16_f32 v190, v40, v41
	v_cvt_pk_bf16_f32 v191, v42, v43
	global_store_dwordx4 v[142:143], v[188:191], off
	v_lshlrev_b32_e32 v228, 16, v208
	v_and_b32_e32 v229, 0xffff0000, v208
	v_lshlrev_b32_e32 v230, 16, v209
	v_and_b32_e32 v231, 0xffff0000, v209
	v_lshlrev_b32_e32 v232, 16, v210
	v_and_b32_e32 v233, 0xffff0000, v210
	v_lshlrev_b32_e32 v234, 16, v211
	v_and_b32_e32 v235, 0xffff0000, v211
	v_pk_add_f32 v[36:37], v[36:37], v[228:229]
	v_pk_add_f32 v[38:39], v[38:39], v[230:231]
	v_pk_add_f32 v[32:33], v[32:33], v[232:233]
	v_pk_add_f32 v[34:35], v[34:35], v[234:235]
	v_pk_fma_f32 v[236:237], v[36:37], v[36:37], v[236:237]
	v_pk_fma_f32 v[236:237], v[38:39], v[38:39], v[236:237]
	v_pk_fma_f32 v[236:237], v[32:33], v[32:33], v[236:237]
	v_pk_fma_f32 v[236:237], v[34:35], v[34:35], v[236:237]
	v_cvt_pk_bf16_f32 v208, v36, v37
	v_cvt_pk_bf16_f32 v209, v38, v39
	v_cvt_pk_bf16_f32 v210, v32, v33
	v_cvt_pk_bf16_f32 v211, v34, v35
	global_store_dwordx4 v[142:143], v[208:211], off offset:256
	s_nop 0
	v_add_f32_e32 v142, v236, v237
	v_lshlrev_b32_e32 v228, 16, v212
	v_and_b32_e32 v229, 0xffff0000, v212
	v_lshlrev_b32_e32 v230, 16, v213
	v_and_b32_e32 v231, 0xffff0000, v213
	v_lshlrev_b32_e32 v232, 16, v214
	v_and_b32_e32 v233, 0xffff0000, v214
	v_lshlrev_b32_e32 v234, 16, v215
	v_and_b32_e32 v235, 0xffff0000, v215
	v_pk_add_f32 v[28:29], v[28:29], v[228:229]
	v_pk_add_f32 v[30:31], v[30:31], v[230:231]
	v_pk_add_f32 v[24:25], v[24:25], v[232:233]
	v_pk_add_f32 v[26:27], v[26:27], v[234:235]
	v_pk_mul_f32 v[236:237], v[28:29], v[28:29]
	v_pk_fma_f32 v[236:237], v[30:31], v[30:31], v[236:237]
	v_pk_fma_f32 v[236:237], v[24:25], v[24:25], v[236:237]
	v_pk_fma_f32 v[236:237], v[26:27], v[26:27], v[236:237]
	v_cvt_pk_bf16_f32 v212, v28, v29
	v_cvt_pk_bf16_f32 v213, v30, v31
	v_cvt_pk_bf16_f32 v214, v24, v25
	v_cvt_pk_bf16_f32 v215, v26, v27
	global_store_dwordx4 v[144:145], v[212:215], off
	v_lshlrev_b32_e32 v228, 16, v216
; __device__ __forceinline__ unsigned cvt_pk_bf16(float lo, float hi) { unsigned r; asm volatile("v_cvt_pk_bf16_f32 %0, %1, %2" : "=v"(r) : "v"(lo), "v"(hi)); return r; }
; __device__ __forceinline__ unsigned cvt_pk_bf16(float lo, float hi) { const f32x2 v = {lo, hi}; const bf16x2_t b = __builtin_convertvector(v, bf16x2_t); return __builtin_bit_cast(unsigned, b); }
;     __device__ __forceinline__ void operator()(const f32x4 (&acc)[2][2][4][2], const Unit& u, int wr, int wc, int fr, int fq) const {
;     ...
;                 const u32x4 b0 = rb[ai][m][0], b1 = rb[ai][m][1];
;                 float ss = 0.f;
; #pragma unroll
;                 for (int bj = 0; bj < 2; ++bj) {
;                     const u32x4 b = bj ? b1 : b0;
;                     f32x4 v0, v1;
;                     v0[0] = __uint_as_float(b.x << 16); v0[1] = __uint_as_float(b.x & 0xffff0000u); v0[2] = __uint_as_float(b.y << 16); v0[3] = __uint_as_float(b.y & 0xffff0000u);
;                     v1[0] = __uint_as_float(b.z << 16); v1[1] = __uint_as_float(b.z & 0xffff0000u); v1[2] = __uint_as_float(b.w << 16); v1[3] = __uint_as_float(b.w & 0xffff0000u);
;                     v0 += acc[ai][bj][m][0] * alpha; v1 += acc[ai][bj][m][1] * alpha;
;                     ss += (v0[0] * v0[0] + v0[1] * v0[1]) + (v0[2] * v0[2] + v0[3] * v0[3]) + (v1[0] * v1[0] + v1[1] * v1[1]) + (v1[2] * v1[2] + v1[3] * v1[3]);
;                     u32x4 w; w.x = cvt_pk_bf16(v0[0], v0[1]); w.y = cvt_pk_bf16(v0[2], v0[3]); w.z = cvt_pk_bf16(v1[0], v1[1]); w.w = cvt_pk_bf16(v1[2], v1[3]);
;                     *(u32x4*)(xp + bj * HALF) = w;
;                 }
;                 ss += __shfl_xor(ss, 16); ss += __shfl_xor(ss, 32);
;                 if (fq == 0) SS[(size_t)r * 16 + u.pn * 4 + wc] = ss;
	v_and_b32_e32 v229, 0xffff0000, v216
	v_lshlrev_b32_e32 v230, 16, v217
	v_and_b32_e32 v231, 0xffff0000, v217
	v_lshlrev_b32_e32 v232, 16, v218
	v_and_b32_e32 v233, 0xffff0000, v218
	v_lshlrev_b32_e32 v234, 16, v219
	v_and_b32_e32 v235, 0xffff0000, v219
	v_pk_add_f32 v[20:21], v[20:21], v[228:229]
	v_pk_add_f32 v[22:23], v[22:23], v[230:231]
	v_pk_add_f32 v[16:17], v[16:17], v[232:233]
	v_pk_add_f32 v[18:19], v[18:19], v[234:235]
	v_pk_fma_f32 v[236:237], v[20:21], v[20:21], v[236:237]
	v_pk_fma_f32 v[236:237], v[22:23], v[22:23], v[236:237]
	v_pk_fma_f32 v[236:237], v[16:17], v[16:17], v[236:237]
	v_pk_fma_f32 v[236:237], v[18:19], v[18:19], v[236:237]
	v_cvt_pk_bf16_f32 v216, v20, v21
	v_cvt_pk_bf16_f32 v217, v22, v23
	v_cvt_pk_bf16_f32 v218, v16, v17
	v_cvt_pk_bf16_f32 v219, v18, v19
	global_store_dwordx4 v[144:145], v[216:219], off offset:256
	s_nop 0
	v_add_f32_e32 v144, v236, v237
	v_lshlrev_b32_e32 v228, 16, v220
	v_and_b32_e32 v229, 0xffff0000, v220
	v_lshlrev_b32_e32 v230, 16, v221
	v_and_b32_e32 v231, 0xffff0000, v221
	v_lshlrev_b32_e32 v232, 16, v222
	v_and_b32_e32 v233, 0xffff0000, v222
	v_lshlrev_b32_e32 v234, 16, v223
	v_and_b32_e32 v235, 0xffff0000, v223
	v_pk_add_f32 v[12:13], v[12:13], v[228:229]
	v_pk_add_f32 v[14:15], v[14:15], v[230:231]
	v_pk_add_f32 v[8:9], v[8:9], v[232:233]
	v_pk_add_f32 v[10:11], v[10:11], v[234:235]
	v_pk_mul_f32 v[236:237], v[12:13], v[12:13]
	v_pk_fma_f32 v[236:237], v[14:15], v[14:15], v[236:237]
	v_pk_fma_f32 v[236:237], v[8:9], v[8:9], v[236:237]
	v_pk_fma_f32 v[236:237], v[10:11], v[10:11], v[236:237]
	v_cvt_pk_bf16_f32 v220, v12, v13
	v_cvt_pk_bf16_f32 v221, v14, v15
	v_cvt_pk_bf16_f32 v222, v8, v9
	v_cvt_pk_bf16_f32 v223, v10, v11
	global_store_dwordx4 v[146:147], v[220:223], off
	v_lshlrev_b32_e32 v228, 16, v224
	v_and_b32_e32 v229, 0xffff0000, v224
	v_lshlrev_b32_e32 v230, 16, v225
	v_and_b32_e32 v231, 0xffff0000, v225
	v_lshlrev_b32_e32 v232, 16, v226
	v_and_b32_e32 v233, 0xffff0000, v226
	v_lshlrev_b32_e32 v234, 16, v227
	v_and_b32_e32 v235, 0xffff0000, v227
	v_pk_add_f32 v[4:5], v[4:5], v[228:229]
	v_pk_add_f32 v[6:7], v[6:7], v[230:231]
	v_pk_add_f32 v[0:1], v[0:1], v[232:233]
	v_pk_add_f32 v[2:3], v[2:3], v[234:235]
	v_pk_fma_f32 v[236:237], v[4:5], v[4:5], v[236:237]
	v_pk_fma_f32 v[236:237], v[6:7], v[6:7], v[236:237]
	v_pk_fma_f32 v[236:237], v[0:1], v[0:1], v[236:237]
	v_pk_fma_f32 v[236:237], v[2:3], v[2:3], v[236:237]
	v_cvt_pk_bf16_f32 v224, v4, v5
	v_cvt_pk_bf16_f32 v225, v6, v7
	v_cvt_pk_bf16_f32 v226, v0, v1
	v_cvt_pk_bf16_f32 v227, v2, v3
	global_store_dwordx4 v[146:147], v[224:227], off offset:256
	s_nop 0
	v_add_f32_e32 v146, v236, v237
	ds_bpermute_b32 v133, v238, v132
	ds_bpermute_b32 v135, v238, v134
	ds_bpermute_b32 v137, v238, v136
	ds_bpermute_b32 v139, v238, v138
	ds_bpermute_b32 v141, v238, v140
	ds_bpermute_b32 v143, v238, v142
	ds_bpermute_b32 v145, v238, v144
	ds_bpermute_b32 v147, v238, v146
	s_waitcnt lgkmcnt(7)
	v_add_f32_e32 v132, v132, v133
	s_waitcnt lgkmcnt(6)
	v_add_f32_e32 v134, v134, v135
	s_waitcnt lgkmcnt(5)
	v_add_f32_e32 v136, v136, v137
	s_waitcnt lgkmcnt(4)
	v_add_f32_e32 v138, v138, v139
	s_waitcnt lgkmcnt(3)
	v_add_f32_e32 v140, v140, v141
	s_waitcnt lgkmcnt(2)
	v_add_f32_e32 v142, v142, v143
	s_waitcnt lgkmcnt(1)
	v_add_f32_e32 v144, v144, v145
	s_waitcnt lgkmcnt(0)
	v_add_f32_e32 v146, v146, v147
	ds_bpermute_b32 v133, v239, v132
	ds_bpermute_b32 v135, v239, v134
	ds_bpermute_b32 v137, v239, v136
	ds_bpermute_b32 v139, v239, v138
	ds_bpermute_b32 v141, v239, v140
	ds_bpermute_b32 v143, v239, v142
	ds_bpermute_b32 v145, v239, v144
	ds_bpermute_b32 v147, v239, v146
	s_waitcnt lgkmcnt(7)
	v_add_f32_e32 v132, v132, v133
	s_waitcnt lgkmcnt(6)
	v_add_f32_e32 v134, v134, v135
	s_waitcnt lgkmcnt(5)
	v_add_f32_e32 v136, v136, v137
	s_waitcnt lgkmcnt(4)
	v_add_f32_e32 v138, v138, v139
	s_waitcnt lgkmcnt(3)
	v_add_f32_e32 v140, v140, v141
	s_waitcnt lgkmcnt(2)
	v_add_f32_e32 v142, v142, v143
	s_waitcnt lgkmcnt(1)
	v_add_f32_e32 v144, v144, v145
	s_waitcnt lgkmcnt(0)
	v_add_f32_e32 v146, v146, v147
	s_and_saveexec_b64 s[88:89], s[0:1]
	global_store_dword v[240:241], v132, off
	global_store_dword v[240:241], v134, off offset:1024
	global_store_dword v[240:241], v136, off offset:2048
	global_store_dword v[240:241], v138, off offset:3072
	s_movk_i32 s84, 0x2000
	v_lshl_add_u64 v[240:241], v[240:241], 0, s[84:85]
	global_store_dword v[240:241], v140, off
	global_store_dword v[240:241], v142, off offset:1024
	global_store_dword v[240:241], v144, off offset:2048
	global_store_dword v[240:241], v146, off offset:3072
	s_or_b64 exec, exec, s[88:89]
	v_and_b32_e32 v112, 64, v246
	v_add_u32_e32 v112, 64, v112
	s_and_b64 vcc, exec, s[6:7]
	s_mov_b64 s[6:7], -1
	s_cbranch_vccnz .LBB0_908
	s_andn2_b64 vcc, exec, s[20:21]
	s_cbranch_vccnz .LBB0_907
	s_barrier
	s_branch .LBB0_907

; __device__ __forceinline__ unsigned cvt_pk_bf16(float lo, float hi) { unsigned r; asm volatile("v_cvt_pk_bf16_f32 %0, %1, %2" : "=v"(r) : "v"(lo), "v"(hi)); return r; }
; __device__ __forceinline__ unsigned cvt_pk_bf16(float lo, float hi) { const f32x2 v = {lo, hi}; const bf16x2_t b = __builtin_convertvector(v, bf16x2_t); return __builtin_bit_cast(unsigned, b); }
;     __device__ __forceinline__ void operator()(const f32x4 (&acc)[2][2][4][2], const Unit& u, int wr, int wc, int fr, int fq) const {
;         const int row0 = u.pm * BM + wr * 64 + fr, col0 = u.pn * BM + wc * 32 + 8 * fq;
;         u32x4 rb[2][4][2];
; #pragma unroll
;         for (int ai = 0; ai < 2; ++ai)
; #pragma unroll
;             for (int m = 0; m < 4; ++m) { const bf16_t* xq = XB + (size_t)(row0 + ai * HALF + m * 16) * 1024 + col0; rb[ai][m][0] = *(const u32x4*)xq; rb[ai][m][1] = *(const u32x4*)(xq + HALF); }
; #pragma unroll
;         for (int ai = 0; ai < 2; ++ai) {
; #pragma unroll
;             for (int m = 0; m < 4; ++m) {
;                 const int r = row0 + ai * HALF + m * 16;
;                 bf16_t* xp = XB + (size_t)r * 1024 + col0;
;                 const u32x4 b0 = rb[ai][m][0], b1 = rb[ai][m][1];
;                 float ss = 0.f;
; #pragma unroll
;                 for (int bj = 0; bj < 2; ++bj) {
;                     const u32x4 b = bj ? b1 : b0;
;                     f32x4 v0, v1;
;                     v0[0] = __uint_as_float(b.x << 16); v0[1] = __uint_as_float(b.x & 0xffff0000u); v0[2] = __uint_as_float(b.y << 16); v0[3] = __uint_as_float(b.y & 0xffff0000u);
;                     v1[0] = __uint_as_float(b.z << 16); v1[1] = __uint_as_float(b.z & 0xffff0000u); v1[2] = __uint_as_float(b.w << 16); v1[3] = __uint_as_float(b.w & 0xffff0000u);
;                     v0 += acc[ai][bj][m][0] * alpha; v1 += acc[ai][bj][m][1] * alpha;
;                     ss += (v0[0] * v0[0] + v0[1] * v0[1]) + (v0[2] * v0[2] + v0[3] * v0[3]) + (v1[0] * v1[0] + v1[1] * v1[1]) + (v1[2] * v1[2] + v1[3] * v1[3]);
;                     u32x4 w; w.x = cvt_pk_bf16(v0[0], v0[1]); w.y = cvt_pk_bf16(v0[2], v0[3]); w.z = cvt_pk_bf16(v1[0], v1[1]); w.w = cvt_pk_bf16(v1[2], v1[3]);
;                     *(u32x4*)(xp + bj * HALF) = w;
.LBB0_1122:
	v_lshl_or_b32 v142, s18, 8, v245
	v_lshl_add_u32 v144, s71, 8, v193
	v_lshlrev_b32_e32 v142, 1, v142
	v_mov_b32_e32 v143, 0
	v_mov_b32_e32 v145, 0
	s_mov_b32 s84, 0x8000
	s_mov_b32 s85, 0
	s_mov_b32 s86, 0x40000
	s_mov_b32 s87, 0
	v_lshl_add_u64 v[146:147], s[34:35], 0, v[142:143]
	v_lshlrev_b32_e32 v232, 11, v144
	v_mov_b32_e32 v233, 0
	v_lshl_add_u64 v[146:147], v[146:147], 0, v[232:233]
	v_lshl_add_u64 v[154:155], v[146:147], 0, s[86:87]
	v_lshl_add_u64 v[148:149], v[146:147], 0, s[84:85]
	v_lshl_add_u64 v[150:151], v[148:149], 0, s[84:85]
	v_lshl_add_u64 v[152:153], v[150:151], 0, s[84:85]
	v_lshl_add_u64 v[156:157], v[154:155], 0, s[84:85]
	v_lshl_add_u64 v[158:159], v[156:157], 0, s[84:85]
	v_lshl_add_u64 v[160:161], v[158:159], 0, s[84:85]
	v_readfirstlane_b32 s101, v192
	s_nop 1
	s_lshr_b32 s101, s101, 6
	v_lshrrev_b32_e32 v236, 5, v246
	v_and_b32_e32 v237, 31, v246
	v_mov_b32_e32 v238, v236
	v_xor_b32_e32 v239, v237, v238
	v_lshlrev_b32_e32 v239, 4, v239
	v_lshl_add_u32 v168, v238, 11, v239
	v_or_b32_e32 v238, 2, v236
	v_xor_b32_e32 v239, v237, v238
	v_lshlrev_b32_e32 v239, 4, v239
	v_lshl_add_u32 v176, v238, 11, v239
	v_or_b32_e32 v238, 4, v236
	v_xor_b32_e32 v239, v237, v238
	v_lshlrev_b32_e32 v239, 4, v239
	v_lshl_add_u32 v184, v238, 11, v239
	v_or_b32_e32 v238, 6, v236
	v_xor_b32_e32 v239, v237, v238
	v_lshlrev_b32_e32 v239, 4, v239
	v_lshl_add_u32 v196, v238, 11, v239
	v_or_b32_e32 v238, 8, v236
	v_xor_b32_e32 v239, v237, v238
	v_lshlrev_b32_e32 v239, 4, v239
	v_lshl_add_u32 v204, v238, 11, v239
	v_or_b32_e32 v238, 10, v236
	v_xor_b32_e32 v239, v237, v238
	v_lshlrev_b32_e32 v239, 4, v239
	v_lshl_add_u32 v212, v238, 11, v239
	v_or_b32_e32 v238, 12, v236
	v_xor_b32_e32 v239, v237, v238
	v_lshlrev_b32_e32 v239, 4, v239
	v_lshl_add_u32 v220, v238, 11, v239
	v_or_b32_e32 v238, 14, v236
	v_xor_b32_e32 v239, v237, v238
	v_lshlrev_b32_e32 v239, 4, v239
	v_lshl_add_u32 v228, v238, 11, v239
	s_lshl_b32 s98, s71, 19
	s_lshl_b32 s99, s101, 15
	s_add_u32 s98, s98, s99
	s_lshl_b32 s99, s18, 9
	s_add_u32 s98, s98, s99
	s_add_u32 s98, s34, s98
	s_addc_u32 s99, s35, 0
	s_lshl_b32 s100, s101, 13
	s_waitcnt vmcnt(0)
	s_barrier
	s_add_i32 m0, s100, 0x0
	s_nop 0
	global_load_lds_dwordx4 v168, s[98:99]
	s_add_i32 m0, s100, 0x400
	s_nop 0
	global_load_lds_dwordx4 v176, s[98:99]
	s_add_i32 m0, s100, 0x800
	s_nop 0
	global_load_lds_dwordx4 v184, s[98:99]
	s_add_i32 m0, s100, 0xc00
	s_nop 0
	global_load_lds_dwordx4 v196, s[98:99]
	s_add_i32 m0, s100, 0x1000
	s_nop 0
	global_load_lds_dwordx4 v204, s[98:99]
	s_add_i32 m0, s100, 0x1400
	s_nop 0
	global_load_lds_dwordx4 v212, s[98:99]
	s_add_i32 m0, s100, 0x1800
	s_nop 0
	global_load_lds_dwordx4 v220, s[98:99]
	s_add_i32 m0, s100, 0x1c00
	s_nop 0
	global_load_lds_dwordx4 v228, s[98:99]
	s_add_u32 s98, s98, 0x40000
	s_addc_u32 s99, s99, 0
	s_add_i32 m0, s100, 0x10000
	s_nop 0
	global_load_lds_dwordx4 v168, s[98:99]
	s_add_i32 m0, s100, 0x10400
	s_nop 0
	global_load_lds_dwordx4 v176, s[98:99]
	s_add_i32 m0, s100, 0x10800
	s_nop 0
	global_load_lds_dwordx4 v184, s[98:99]
	s_add_i32 m0, s100, 0x10c00
	s_nop 0
	global_load_lds_dwordx4 v196, s[98:99]
	s_add_i32 m0, s100, 0x11000
	s_nop 0
	global_load_lds_dwordx4 v204, s[98:99]
	s_add_i32 m0, s100, 0x11400
	s_nop 0
	global_load_lds_dwordx4 v212, s[98:99]
	s_add_i32 m0, s100, 0x11800
	s_nop 0
	global_load_lds_dwordx4 v220, s[98:99]
	s_add_i32 m0, s100, 0x11c00
	s_nop 0
	global_load_lds_dwordx4 v228, s[98:99]
	v_lshrrev_b32_e32 v234, 3, v245
	v_and_b32_e32 v235, 15, v193
	v_xor_b32_e32 v234, v234, v235
	v_lshlrev_b32_e32 v234, 4, v234
	v_lshl_add_u32 v232, v193, 9, v234
	v_add_u32_e32 v242, 0x10000, v232
	s_waitcnt vmcnt(8)
	s_barrier
	ds_read_b128 v[164:167], v232
	ds_read_b128 v[168:171], v232 offset:256
	ds_read_b128 v[172:175], v232 offset:8192
	ds_read_b128 v[176:179], v232 offset:8448
	ds_read_b128 v[180:183], v232 offset:16384
	ds_read_b128 v[184:187], v232 offset:16640
	ds_read_b128 v[188:191], v232 offset:24576
	ds_read_b128 v[196:199], v232 offset:24832
	s_waitcnt lgkmcnt(0)
	v_xor_b32_e32 v194, 16, v246
	v_xor_b32_e32 v195, 32, v246
	v_lshlrev_b32_e32 v194, 2, v194
	v_lshlrev_b32_e32 v195, 2, v195
	s_lshl_b32 s90, s18, 2
	s_add_i32 s90, s90, s60
	s_lshl_b32 s90, s90, 2
	s_mov_b32 s91, 0
	v_lshlrev_b32_e32 v234, 6, v144
	v_mov_b32_e32 v235, 0
	v_lshl_add_u64 v[240:241], s[44:45], 0, v[234:235]
	v_lshl_add_u64 v[240:241], v[240:241], 0, s[90:91]
	v_lshlrev_b32_e32 v232, 16, v164
	v_and_b32_e32 v233, 0xffff0000, v164
	v_lshlrev_b32_e32 v234, 16, v165
	v_and_b32_e32 v235, 0xffff0000, v165
	v_lshlrev_b32_e32 v236, 16, v166
	v_and_b32_e32 v237, 0xffff0000, v166
	v_lshlrev_b32_e32 v238, 16, v167
	v_and_b32_e32 v239, 0xffff0000, v167
	v_pk_fma_f32 v[124:125], v[124:125], 0.5, v[232:233] op_sel_hi:[1,0,1]
	v_pk_fma_f32 v[126:127], v[126:127], 0.5, v[234:235] op_sel_hi:[1,0,1]
	v_pk_fma_f32 v[120:121], v[120:121], 0.5, v[236:237] op_sel_hi:[1,0,1]
	v_pk_fma_f32 v[122:123], v[122:123], 0.5, v[238:239] op_sel_hi:[1,0,1]
	v_pk_mul_f32 v[162:163], v[124:125], v[124:125]
	v_pk_fma_f32 v[162:163], v[126:127], v[126:127], v[162:163]
	v_pk_fma_f32 v[162:163], v[120:121], v[120:121], v[162:163]
	v_pk_fma_f32 v[162:163], v[122:123], v[122:123], v[162:163]
	v_cvt_pk_bf16_f32 v164, v124, v125
	v_cvt_pk_bf16_f32 v165, v126, v127
	v_cvt_pk_bf16_f32 v166, v120, v121
	v_cvt_pk_bf16_f32 v167, v122, v123
	global_store_dwordx4 v[146:147], v[164:167], off
	v_lshlrev_b32_e32 v232, 16, v168
	v_and_b32_e32 v233, 0xffff0000, v168
	v_lshlrev_b32_e32 v234, 16, v169
	v_and_b32_e32 v235, 0xffff0000, v169
	v_lshlrev_b32_e32 v236, 16, v170
	v_and_b32_e32 v237, 0xffff0000, v170
; __device__ __forceinline__ unsigned cvt_pk_bf16(float lo, float hi) { unsigned r; asm volatile("v_cvt_pk_bf16_f32 %0, %1, %2" : "=v"(r) : "v"(lo), "v"(hi)); return r; }
; __device__ __forceinline__ unsigned cvt_pk_bf16(float lo, float hi) { const f32x2 v = {lo, hi}; const bf16x2_t b = __builtin_convertvector(v, bf16x2_t); return __builtin_bit_cast(unsigned, b); }
;     __device__ __forceinline__ void operator()(const f32x4 (&acc)[2][2][4][2], const Unit& u, int wr, int wc, int fr, int fq) const {
;     ...
;                 const u32x4 b0 = rb[ai][m][0], b1 = rb[ai][m][1];
;                 float ss = 0.f;
; #pragma unroll
;                 for (int bj = 0; bj < 2; ++bj) {
;                     const u32x4 b = bj ? b1 : b0;
;                     f32x4 v0, v1;
;                     v0[0] = __uint_as_float(b.x << 16); v0[1] = __uint_as_float(b.x & 0xffff0000u); v0[2] = __uint_as_float(b.y << 16); v0[3] = __uint_as_float(b.y & 0xffff0000u);
;                     v1[0] = __uint_as_float(b.z << 16); v1[1] = __uint_as_float(b.z & 0xffff0000u); v1[2] = __uint_as_float(b.w << 16); v1[3] = __uint_as_float(b.w & 0xffff0000u);
;                     v0 += acc[ai][bj][m][0] * alpha; v1 += acc[ai][bj][m][1] * alpha;
;                     ss += (v0[0] * v0[0] + v0[1] * v0[1]) + (v0[2] * v0[2] + v0[3] * v0[3]) + (v1[0] * v1[0] + v1[1] * v1[1]) + (v1[2] * v1[2] + v1[3] * v1[3]);
;                     u32x4 w; w.x = cvt_pk_bf16(v0[0], v0[1]); w.y = cvt_pk_bf16(v0[2], v0[3]); w.z = cvt_pk_bf16(v1[0], v1[1]); w.w = cvt_pk_bf16(v1[2], v1[3]);
;                     *(u32x4*)(xp + bj * HALF) = w;
	v_lshlrev_b32_e32 v238, 16, v171
	v_and_b32_e32 v239, 0xffff0000, v171
	v_pk_fma_f32 v[108:109], v[108:109], 0.5, v[232:233] op_sel_hi:[1,0,1]
	v_pk_fma_f32 v[110:111], v[110:111], 0.5, v[234:235] op_sel_hi:[1,0,1]
	v_pk_fma_f32 v[100:101], v[100:101], 0.5, v[236:237] op_sel_hi:[1,0,1]
	v_pk_fma_f32 v[102:103], v[102:103], 0.5, v[238:239] op_sel_hi:[1,0,1]
	v_pk_fma_f32 v[162:163], v[108:109], v[108:109], v[162:163]
	v_pk_fma_f32 v[162:163], v[110:111], v[110:111], v[162:163]
	v_pk_fma_f32 v[162:163], v[100:101], v[100:101], v[162:163]
	v_pk_fma_f32 v[162:163], v[102:103], v[102:103], v[162:163]
	v_cvt_pk_bf16_f32 v168, v108, v109
	v_cvt_pk_bf16_f32 v169, v110, v111
	v_cvt_pk_bf16_f32 v170, v100, v101
	v_cvt_pk_bf16_f32 v171, v102, v103
	global_store_dwordx4 v[146:147], v[168:171], off offset:256
	s_nop 0
	v_add_f32_e32 v146, v162, v163
	v_lshlrev_b32_e32 v232, 16, v172
	v_and_b32_e32 v233, 0xffff0000, v172
	v_lshlrev_b32_e32 v234, 16, v173
	v_and_b32_e32 v235, 0xffff0000, v173
	v_lshlrev_b32_e32 v236, 16, v174
	v_and_b32_e32 v237, 0xffff0000, v174
	v_lshlrev_b32_e32 v238, 16, v175
	v_and_b32_e32 v239, 0xffff0000, v175
	v_pk_fma_f32 v[116:117], v[116:117], 0.5, v[232:233] op_sel_hi:[1,0,1]
	v_pk_fma_f32 v[118:119], v[118:119], 0.5, v[234:235] op_sel_hi:[1,0,1]
	v_pk_fma_f32 v[112:113], v[112:113], 0.5, v[236:237] op_sel_hi:[1,0,1]
	v_pk_fma_f32 v[114:115], v[114:115], 0.5, v[238:239] op_sel_hi:[1,0,1]
	v_pk_mul_f32 v[162:163], v[116:117], v[116:117]
	v_pk_fma_f32 v[162:163], v[118:119], v[118:119], v[162:163]
	v_pk_fma_f32 v[162:163], v[112:113], v[112:113], v[162:163]
	v_pk_fma_f32 v[162:163], v[114:115], v[114:115], v[162:163]
	v_cvt_pk_bf16_f32 v172, v116, v117
	v_cvt_pk_bf16_f32 v173, v118, v119
	v_cvt_pk_bf16_f32 v174, v112, v113
	v_cvt_pk_bf16_f32 v175, v114, v115
	global_store_dwordx4 v[148:149], v[172:175], off
	v_lshlrev_b32_e32 v232, 16, v176
	v_and_b32_e32 v233, 0xffff0000, v176
	v_lshlrev_b32_e32 v234, 16, v177
	v_and_b32_e32 v235, 0xffff0000, v177
	v_lshlrev_b32_e32 v236, 16, v178
	v_and_b32_e32 v237, 0xffff0000, v178
	v_lshlrev_b32_e32 v238, 16, v179
	v_and_b32_e32 v239, 0xffff0000, v179
	v_pk_fma_f32 v[92:93], v[92:93], 0.5, v[232:233] op_sel_hi:[1,0,1]
	v_pk_fma_f32 v[94:95], v[94:95], 0.5, v[234:235] op_sel_hi:[1,0,1]
	v_pk_fma_f32 v[84:85], v[84:85], 0.5, v[236:237] op_sel_hi:[1,0,1]
	v_pk_fma_f32 v[86:87], v[86:87], 0.5, v[238:239] op_sel_hi:[1,0,1]
	v_pk_fma_f32 v[162:163], v[92:93], v[92:93], v[162:163]
	v_pk_fma_f32 v[162:163], v[94:95], v[94:95], v[162:163]
	v_pk_fma_f32 v[162:163], v[84:85], v[84:85], v[162:163]
	v_pk_fma_f32 v[162:163], v[86:87], v[86:87], v[162:163]
	v_cvt_pk_bf16_f32 v176, v92, v93
	v_cvt_pk_bf16_f32 v177, v94, v95
	v_cvt_pk_bf16_f32 v178, v84, v85
	v_cvt_pk_bf16_f32 v179, v86, v87
	global_store_dwordx4 v[148:149], v[176:179], off offset:256
	s_nop 0
	v_add_f32_e32 v148, v162, v163
	v_lshlrev_b32_e32 v232, 16, v180
	v_and_b32_e32 v233, 0xffff0000, v180
	v_lshlrev_b32_e32 v234, 16, v181
	v_and_b32_e32 v235, 0xffff0000, v181
	v_lshlrev_b32_e32 v236, 16, v182
	v_and_b32_e32 v237, 0xffff0000, v182
	v_lshlrev_b32_e32 v238, 16, v183
	v_and_b32_e32 v239, 0xffff0000, v183
	v_pk_fma_f32 v[104:105], v[104:105], 0.5, v[232:233] op_sel_hi:[1,0,1]
	v_pk_fma_f32 v[106:107], v[106:107], 0.5, v[234:235] op_sel_hi:[1,0,1]
	v_pk_fma_f32 v[96:97], v[96:97], 0.5, v[236:237] op_sel_hi:[1,0,1]
	v_pk_fma_f32 v[98:99], v[98:99], 0.5, v[238:239] op_sel_hi:[1,0,1]
	v_pk_mul_f32 v[162:163], v[104:105], v[104:105]
	v_pk_fma_f32 v[162:163], v[106:107], v[106:107], v[162:163]
	v_pk_fma_f32 v[162:163], v[96:97], v[96:97], v[162:163]
	v_pk_fma_f32 v[162:163], v[98:99], v[98:99], v[162:163]
	v_cvt_pk_bf16_f32 v180, v104, v105
	v_cvt_pk_bf16_f32 v181, v106, v107
	v_cvt_pk_bf16_f32 v182, v96, v97
	v_cvt_pk_bf16_f32 v183, v98, v99
	global_store_dwordx4 v[150:151], v[180:183], off
	v_lshlrev_b32_e32 v232, 16, v184
	v_and_b32_e32 v233, 0xffff0000, v184
	v_lshlrev_b32_e32 v234, 16, v185
	v_and_b32_e32 v235, 0xffff0000, v185
	v_lshlrev_b32_e32 v236, 16, v186
	v_and_b32_e32 v237, 0xffff0000, v186
	v_lshlrev_b32_e32 v238, 16, v187
	v_and_b32_e32 v239, 0xffff0000, v187
	v_pk_fma_f32 v[76:77], v[76:77], 0.5, v[232:233] op_sel_hi:[1,0,1]
	v_pk_fma_f32 v[78:79], v[78:79], 0.5, v[234:235] op_sel_hi:[1,0,1]
	v_pk_fma_f32 v[72:73], v[72:73], 0.5, v[236:237] op_sel_hi:[1,0,1]
	v_pk_fma_f32 v[74:75], v[74:75], 0.5, v[238:239] op_sel_hi:[1,0,1]
	v_pk_fma_f32 v[162:163], v[76:77], v[76:77], v[162:163]
	v_pk_fma_f32 v[162:163], v[78:79], v[78:79], v[162:163]
	v_pk_fma_f32 v[162:163], v[72:73], v[72:73], v[162:163]
	v_pk_fma_f32 v[162:163], v[74:75], v[74:75], v[162:163]
	v_cvt_pk_bf16_f32 v184, v76, v77
	v_cvt_pk_bf16_f32 v185, v78, v79
	v_cvt_pk_bf16_f32 v186, v72, v73
	v_cvt_pk_bf16_f32 v187, v74, v75
	global_store_dwordx4 v[150:151], v[184:187], off offset:256
	s_nop 0
	v_add_f32_e32 v150, v162, v163
	v_lshlrev_b32_e32 v232, 16, v188
	v_and_b32_e32 v233, 0xffff0000, v188
	v_lshlrev_b32_e32 v234, 16, v189
	v_and_b32_e32 v235, 0xffff0000, v189
	v_lshlrev_b32_e32 v236, 16, v190
	v_and_b32_e32 v237, 0xffff0000, v190
	v_lshlrev_b32_e32 v238, 16, v191
	v_and_b32_e32 v239, 0xffff0000, v191
	v_pk_fma_f32 v[88:89], v[88:89], 0.5, v[232:233] op_sel_hi:[1,0,1]
	v_pk_fma_f32 v[90:91], v[90:91], 0.5, v[234:235] op_sel_hi:[1,0,1]
	v_pk_fma_f32 v[80:81], v[80:81], 0.5, v[236:237] op_sel_hi:[1,0,1]
	v_pk_fma_f32 v[82:83], v[82:83], 0.5, v[238:239] op_sel_hi:[1,0,1]
	v_pk_mul_f32 v[162:163], v[88:89], v[88:89]
	v_pk_fma_f32 v[162:163], v[90:91], v[90:91], v[162:163]
	v_pk_fma_f32 v[162:163], v[80:81], v[80:81], v[162:163]
	v_pk_fma_f32 v[162:163], v[82:83], v[82:83], v[162:163]
	v_cvt_pk_bf16_f32 v188, v88, v89
	v_cvt_pk_bf16_f32 v189, v90, v91
	v_cvt_pk_bf16_f32 v190, v80, v81
	v_cvt_pk_bf16_f32 v191, v82, v83
	global_store_dwordx4 v[152:153], v[188:191], off
	v_lshlrev_b32_e32 v232, 16, v196
	v_and_b32_e32 v233, 0xffff0000, v196
	v_lshlrev_b32_e32 v234, 16, v197
	v_and_b32_e32 v235, 0xffff0000, v197
	v_lshlrev_b32_e32 v236, 16, v198
	v_and_b32_e32 v237, 0xffff0000, v198
	v_lshlrev_b32_e32 v238, 16, v199
	v_and_b32_e32 v239, 0xffff0000, v199
	v_pk_fma_f32 v[68:69], v[68:69], 0.5, v[232:233] op_sel_hi:[1,0,1]
	v_pk_fma_f32 v[70:71], v[70:71], 0.5, v[234:235] op_sel_hi:[1,0,1]
	v_pk_fma_f32 v[64:65], v[64:65], 0.5, v[236:237] op_sel_hi:[1,0,1]
	v_pk_fma_f32 v[66:67], v[66:67], 0.5, v[238:239] op_sel_hi:[1,0,1]
	v_pk_fma_f32 v[162:163], v[68:69], v[68:69], v[162:163]
	v_pk_fma_f32 v[162:163], v[70:71], v[70:71], v[162:163]
	v_pk_fma_f32 v[162:163], v[64:65], v[64:65], v[162:163]
	v_pk_fma_f32 v[162:163], v[66:67], v[66:67], v[162:163]
	v_cvt_pk_bf16_f32 v196, v68, v69
	v_cvt_pk_bf16_f32 v197, v70, v71
	v_cvt_pk_bf16_f32 v198, v64, v65
	v_cvt_pk_bf16_f32 v199, v66, v67
	global_store_dwordx4 v[152:153], v[196:199], off offset:256
	s_nop 0
	v_add_f32_e32 v152, v162, v163
	s_waitcnt vmcnt(8)
	s_barrier
; __device__ __forceinline__ unsigned cvt_pk_bf16(float lo, float hi) { unsigned r; asm volatile("v_cvt_pk_bf16_f32 %0, %1, %2" : "=v"(r) : "v"(lo), "v"(hi)); return r; }
; __device__ __forceinline__ unsigned cvt_pk_bf16(float lo, float hi) { const f32x2 v = {lo, hi}; const bf16x2_t b = __builtin_convertvector(v, bf16x2_t); return __builtin_bit_cast(unsigned, b); }
;     __device__ __forceinline__ void operator()(const f32x4 (&acc)[2][2][4][2], const Unit& u, int wr, int wc, int fr, int fq) const {
;     ...
;                 const u32x4 b0 = rb[ai][m][0], b1 = rb[ai][m][1];
;                 float ss = 0.f;
; #pragma unroll
;                 for (int bj = 0; bj < 2; ++bj) {
;                     const u32x4 b = bj ? b1 : b0;
;                     f32x4 v0, v1;
;                     v0[0] = __uint_as_float(b.x << 16); v0[1] = __uint_as_float(b.x & 0xffff0000u); v0[2] = __uint_as_float(b.y << 16); v0[3] = __uint_as_float(b.y & 0xffff0000u);
;                     v1[0] = __uint_as_float(b.z << 16); v1[1] = __uint_as_float(b.z & 0xffff0000u); v1[2] = __uint_as_float(b.w << 16); v1[3] = __uint_as_float(b.w & 0xffff0000u);
;                     v0 += acc[ai][bj][m][0] * alpha; v1 += acc[ai][bj][m][1] * alpha;
;                     ss += (v0[0] * v0[0] + v0[1] * v0[1]) + (v0[2] * v0[2] + v0[3] * v0[3]) + (v1[0] * v1[0] + v1[1] * v1[1]) + (v1[2] * v1[2] + v1[3] * v1[3]);
;                     u32x4 w; w.x = cvt_pk_bf16(v0[0], v0[1]); w.y = cvt_pk_bf16(v0[2], v0[3]); w.z = cvt_pk_bf16(v1[0], v1[1]); w.w = cvt_pk_bf16(v1[2], v1[3]);
;                     *(u32x4*)(xp + bj * HALF) = w;
	ds_read_b128 v[200:203], v242
	ds_read_b128 v[204:207], v242 offset:256
	ds_read_b128 v[208:211], v242 offset:8192
	ds_read_b128 v[212:215], v242 offset:8448
	ds_read_b128 v[216:219], v242 offset:16384
	ds_read_b128 v[220:223], v242 offset:16640
	ds_read_b128 v[224:227], v242 offset:24576
	ds_read_b128 v[228:231], v242 offset:24832
	s_waitcnt lgkmcnt(0)
	v_lshlrev_b32_e32 v232, 16, v200
	v_and_b32_e32 v233, 0xffff0000, v200
	v_lshlrev_b32_e32 v234, 16, v201
	v_and_b32_e32 v235, 0xffff0000, v201
	v_lshlrev_b32_e32 v236, 16, v202
	v_and_b32_e32 v237, 0xffff0000, v202
	v_lshlrev_b32_e32 v238, 16, v203
	v_and_b32_e32 v239, 0xffff0000, v203
	v_pk_fma_f32 v[60:61], v[60:61], 0.5, v[232:233] op_sel_hi:[1,0,1]
	v_pk_fma_f32 v[62:63], v[62:63], 0.5, v[234:235] op_sel_hi:[1,0,1]
	v_pk_fma_f32 v[56:57], v[56:57], 0.5, v[236:237] op_sel_hi:[1,0,1]
	v_pk_fma_f32 v[58:59], v[58:59], 0.5, v[238:239] op_sel_hi:[1,0,1]
	v_pk_mul_f32 v[162:163], v[60:61], v[60:61]
	v_pk_fma_f32 v[162:163], v[62:63], v[62:63], v[162:163]
	v_pk_fma_f32 v[162:163], v[56:57], v[56:57], v[162:163]
	v_pk_fma_f32 v[162:163], v[58:59], v[58:59], v[162:163]
	v_cvt_pk_bf16_f32 v200, v60, v61
	v_cvt_pk_bf16_f32 v201, v62, v63
	v_cvt_pk_bf16_f32 v202, v56, v57
	v_cvt_pk_bf16_f32 v203, v58, v59
	global_store_dwordx4 v[154:155], v[200:203], off
	v_lshlrev_b32_e32 v232, 16, v204
	v_and_b32_e32 v233, 0xffff0000, v204
	v_lshlrev_b32_e32 v234, 16, v205
	v_and_b32_e32 v235, 0xffff0000, v205
	v_lshlrev_b32_e32 v236, 16, v206
	v_and_b32_e32 v237, 0xffff0000, v206
	v_lshlrev_b32_e32 v238, 16, v207
	v_and_b32_e32 v239, 0xffff0000, v207
	v_pk_fma_f32 v[44:45], v[44:45], 0.5, v[232:233] op_sel_hi:[1,0,1]
	v_pk_fma_f32 v[46:47], v[46:47], 0.5, v[234:235] op_sel_hi:[1,0,1]
	v_pk_fma_f32 v[36:37], v[36:37], 0.5, v[236:237] op_sel_hi:[1,0,1]
	v_pk_fma_f32 v[38:39], v[38:39], 0.5, v[238:239] op_sel_hi:[1,0,1]
	v_pk_fma_f32 v[162:163], v[44:45], v[44:45], v[162:163]
	v_pk_fma_f32 v[162:163], v[46:47], v[46:47], v[162:163]
	v_pk_fma_f32 v[162:163], v[36:37], v[36:37], v[162:163]
	v_pk_fma_f32 v[162:163], v[38:39], v[38:39], v[162:163]
	v_cvt_pk_bf16_f32 v204, v44, v45
	v_cvt_pk_bf16_f32 v205, v46, v47
	v_cvt_pk_bf16_f32 v206, v36, v37
	v_cvt_pk_bf16_f32 v207, v38, v39
	global_store_dwordx4 v[154:155], v[204:207], off offset:256
	s_nop 0
	v_add_f32_e32 v154, v162, v163
	v_lshlrev_b32_e32 v232, 16, v208
	v_and_b32_e32 v233, 0xffff0000, v208
	v_lshlrev_b32_e32 v234, 16, v209
	v_and_b32_e32 v235, 0xffff0000, v209
	v_lshlrev_b32_e32 v236, 16, v210
	v_and_b32_e32 v237, 0xffff0000, v210
	v_lshlrev_b32_e32 v238, 16, v211
	v_and_b32_e32 v239, 0xffff0000, v211
	v_pk_fma_f32 v[52:53], v[52:53], 0.5, v[232:233] op_sel_hi:[1,0,1]
	v_pk_fma_f32 v[54:55], v[54:55], 0.5, v[234:235] op_sel_hi:[1,0,1]
	v_pk_fma_f32 v[48:49], v[48:49], 0.5, v[236:237] op_sel_hi:[1,0,1]
	v_pk_fma_f32 v[50:51], v[50:51], 0.5, v[238:239] op_sel_hi:[1,0,1]
	v_pk_mul_f32 v[162:163], v[52:53], v[52:53]
	v_pk_fma_f32 v[162:163], v[54:55], v[54:55], v[162:163]
	v_pk_fma_f32 v[162:163], v[48:49], v[48:49], v[162:163]
	v_pk_fma_f32 v[162:163], v[50:51], v[50:51], v[162:163]
	v_cvt_pk_bf16_f32 v208, v52, v53
	v_cvt_pk_bf16_f32 v209, v54, v55
	v_cvt_pk_bf16_f32 v210, v48, v49
	v_cvt_pk_bf16_f32 v211, v50, v51
	global_store_dwordx4 v[156:157], v[208:211], off
	v_lshlrev_b32_e32 v232, 16, v212
	v_and_b32_e32 v233, 0xffff0000, v212
	v_lshlrev_b32_e32 v234, 16, v213
	v_and_b32_e32 v235, 0xffff0000, v213
	v_lshlrev_b32_e32 v236, 16, v214
	v_and_b32_e32 v237, 0xffff0000, v214
	v_lshlrev_b32_e32 v238, 16, v215
	v_and_b32_e32 v239, 0xffff0000, v215
	v_pk_fma_f32 v[28:29], v[28:29], 0.5, v[232:233] op_sel_hi:[1,0,1]
	v_pk_fma_f32 v[30:31], v[30:31], 0.5, v[234:235] op_sel_hi:[1,0,1]
	v_pk_fma_f32 v[20:21], v[20:21], 0.5, v[236:237] op_sel_hi:[1,0,1]
	v_pk_fma_f32 v[22:23], v[22:23], 0.5, v[238:239] op_sel_hi:[1,0,1]
	v_pk_fma_f32 v[162:163], v[28:29], v[28:29], v[162:163]
	v_pk_fma_f32 v[162:163], v[30:31], v[30:31], v[162:163]
	v_pk_fma_f32 v[162:163], v[20:21], v[20:21], v[162:163]
	v_pk_fma_f32 v[162:163], v[22:23], v[22:23], v[162:163]
	v_cvt_pk_bf16_f32 v212, v28, v29
	v_cvt_pk_bf16_f32 v213, v30, v31
	v_cvt_pk_bf16_f32 v214, v20, v21
	v_cvt_pk_bf16_f32 v215, v22, v23
	global_store_dwordx4 v[156:157], v[212:215], off offset:256
	s_nop 0
	v_add_f32_e32 v156, v162, v163
	v_lshlrev_b32_e32 v232, 16, v216
	v_and_b32_e32 v233, 0xffff0000, v216
	v_lshlrev_b32_e32 v234, 16, v217
	v_and_b32_e32 v235, 0xffff0000, v217
	v_lshlrev_b32_e32 v236, 16, v218
	v_and_b32_e32 v237, 0xffff0000, v218
	v_lshlrev_b32_e32 v238, 16, v219
	v_and_b32_e32 v239, 0xffff0000, v219
	v_pk_fma_f32 v[40:41], v[40:41], 0.5, v[232:233] op_sel_hi:[1,0,1]
	v_pk_fma_f32 v[42:43], v[42:43], 0.5, v[234:235] op_sel_hi:[1,0,1]
	v_pk_fma_f32 v[32:33], v[32:33], 0.5, v[236:237] op_sel_hi:[1,0,1]
	v_pk_fma_f32 v[34:35], v[34:35], 0.5, v[238:239] op_sel_hi:[1,0,1]
	v_pk_mul_f32 v[162:163], v[40:41], v[40:41]
	v_pk_fma_f32 v[162:163], v[42:43], v[42:43], v[162:163]
	v_pk_fma_f32 v[162:163], v[32:33], v[32:33], v[162:163]
	v_pk_fma_f32 v[162:163], v[34:35], v[34:35], v[162:163]
	v_cvt_pk_bf16_f32 v216, v40, v41
	v_cvt_pk_bf16_f32 v217, v42, v43
	v_cvt_pk_bf16_f32 v218, v32, v33
; __device__ __forceinline__ unsigned cvt_pk_bf16(float lo, float hi) { unsigned r; asm volatile("v_cvt_pk_bf16_f32 %0, %1, %2" : "=v"(r) : "v"(lo), "v"(hi)); return r; }
; __device__ __forceinline__ unsigned cvt_pk_bf16(float lo, float hi) { const f32x2 v = {lo, hi}; const bf16x2_t b = __builtin_convertvector(v, bf16x2_t); return __builtin_bit_cast(unsigned, b); }
;     __device__ __forceinline__ void operator()(const f32x4 (&acc)[2][2][4][2], const Unit& u, int wr, int wc, int fr, int fq) const {
;     ...
;                 const u32x4 b0 = rb[ai][m][0], b1 = rb[ai][m][1];
;                 float ss = 0.f;
; #pragma unroll
;                 for (int bj = 0; bj < 2; ++bj) {
;                     const u32x4 b = bj ? b1 : b0;
;                     f32x4 v0, v1;
;                     v0[0] = __uint_as_float(b.x << 16); v0[1] = __uint_as_float(b.x & 0xffff0000u); v0[2] = __uint_as_float(b.y << 16); v0[3] = __uint_as_float(b.y & 0xffff0000u);
;                     v1[0] = __uint_as_float(b.z << 16); v1[1] = __uint_as_float(b.z & 0xffff0000u); v1[2] = __uint_as_float(b.w << 16); v1[3] = __uint_as_float(b.w & 0xffff0000u);
;                     v0 += acc[ai][bj][m][0] * alpha; v1 += acc[ai][bj][m][1] * alpha;
;                     ss += (v0[0] * v0[0] + v0[1] * v0[1]) + (v0[2] * v0[2] + v0[3] * v0[3]) + (v1[0] * v1[0] + v1[1] * v1[1]) + (v1[2] * v1[2] + v1[3] * v1[3]);
;                     u32x4 w; w.x = cvt_pk_bf16(v0[0], v0[1]); w.y = cvt_pk_bf16(v0[2], v0[3]); w.z = cvt_pk_bf16(v1[0], v1[1]); w.w = cvt_pk_bf16(v1[2], v1[3]);
;                     *(u32x4*)(xp + bj * HALF) = w;
;                 }
;                 ss += __shfl_xor(ss, 16); ss += __shfl_xor(ss, 32);
;                 if (fq == 0) SS[(size_t)r * 16 + u.pn * 4 + wc] = ss;
;             }
	v_cvt_pk_bf16_f32 v219, v34, v35
	global_store_dwordx4 v[158:159], v[216:219], off
	v_lshlrev_b32_e32 v232, 16, v220
	v_and_b32_e32 v233, 0xffff0000, v220
	v_lshlrev_b32_e32 v234, 16, v221
	v_and_b32_e32 v235, 0xffff0000, v221
	v_lshlrev_b32_e32 v236, 16, v222
	v_and_b32_e32 v237, 0xffff0000, v222
	v_lshlrev_b32_e32 v238, 16, v223
	v_and_b32_e32 v239, 0xffff0000, v223
	v_pk_fma_f32 v[12:13], v[12:13], 0.5, v[232:233] op_sel_hi:[1,0,1]
	v_pk_fma_f32 v[14:15], v[14:15], 0.5, v[234:235] op_sel_hi:[1,0,1]
	v_pk_fma_f32 v[8:9], v[8:9], 0.5, v[236:237] op_sel_hi:[1,0,1]
	v_pk_fma_f32 v[10:11], v[10:11], 0.5, v[238:239] op_sel_hi:[1,0,1]
	v_pk_fma_f32 v[162:163], v[12:13], v[12:13], v[162:163]
	v_pk_fma_f32 v[162:163], v[14:15], v[14:15], v[162:163]
	v_pk_fma_f32 v[162:163], v[8:9], v[8:9], v[162:163]
	v_pk_fma_f32 v[162:163], v[10:11], v[10:11], v[162:163]
	v_cvt_pk_bf16_f32 v220, v12, v13
	v_cvt_pk_bf16_f32 v221, v14, v15
	v_cvt_pk_bf16_f32 v222, v8, v9
	v_cvt_pk_bf16_f32 v223, v10, v11
	global_store_dwordx4 v[158:159], v[220:223], off offset:256
	s_nop 0
	v_add_f32_e32 v158, v162, v163
	v_lshlrev_b32_e32 v232, 16, v224
	v_and_b32_e32 v233, 0xffff0000, v224
	v_lshlrev_b32_e32 v234, 16, v225
	v_and_b32_e32 v235, 0xffff0000, v225
	v_lshlrev_b32_e32 v236, 16, v226
	v_and_b32_e32 v237, 0xffff0000, v226
	v_lshlrev_b32_e32 v238, 16, v227
	v_and_b32_e32 v239, 0xffff0000, v227
	v_pk_fma_f32 v[24:25], v[24:25], 0.5, v[232:233] op_sel_hi:[1,0,1]
	v_pk_fma_f32 v[26:27], v[26:27], 0.5, v[234:235] op_sel_hi:[1,0,1]
	v_pk_fma_f32 v[16:17], v[16:17], 0.5, v[236:237] op_sel_hi:[1,0,1]
	v_pk_fma_f32 v[18:19], v[18:19], 0.5, v[238:239] op_sel_hi:[1,0,1]
	v_pk_mul_f32 v[162:163], v[24:25], v[24:25]
	v_pk_fma_f32 v[162:163], v[26:27], v[26:27], v[162:163]
	v_pk_fma_f32 v[162:163], v[16:17], v[16:17], v[162:163]
	v_pk_fma_f32 v[162:163], v[18:19], v[18:19], v[162:163]
	v_cvt_pk_bf16_f32 v224, v24, v25
	v_cvt_pk_bf16_f32 v225, v26, v27
	v_cvt_pk_bf16_f32 v226, v16, v17
	v_cvt_pk_bf16_f32 v227, v18, v19
	global_store_dwordx4 v[160:161], v[224:227], off
	v_lshlrev_b32_e32 v232, 16, v228
	v_and_b32_e32 v233, 0xffff0000, v228
	v_lshlrev_b32_e32 v234, 16, v229
	v_and_b32_e32 v235, 0xffff0000, v229
	v_lshlrev_b32_e32 v236, 16, v230
	v_and_b32_e32 v237, 0xffff0000, v230
	v_lshlrev_b32_e32 v238, 16, v231
	v_and_b32_e32 v239, 0xffff0000, v231
	v_pk_fma_f32 v[4:5], v[4:5], 0.5, v[232:233] op_sel_hi:[1,0,1]
	v_pk_fma_f32 v[6:7], v[6:7], 0.5, v[234:235] op_sel_hi:[1,0,1]
	v_pk_fma_f32 v[0:1], v[0:1], 0.5, v[236:237] op_sel_hi:[1,0,1]
	v_pk_fma_f32 v[2:3], v[2:3], 0.5, v[238:239] op_sel_hi:[1,0,1]
	v_pk_fma_f32 v[162:163], v[4:5], v[4:5], v[162:163]
	v_pk_fma_f32 v[162:163], v[6:7], v[6:7], v[162:163]
	v_pk_fma_f32 v[162:163], v[0:1], v[0:1], v[162:163]
	v_pk_fma_f32 v[162:163], v[2:3], v[2:3], v[162:163]
	v_cvt_pk_bf16_f32 v228, v4, v5
	v_cvt_pk_bf16_f32 v229, v6, v7
	v_cvt_pk_bf16_f32 v230, v0, v1
	v_cvt_pk_bf16_f32 v231, v2, v3
	global_store_dwordx4 v[160:161], v[228:231], off offset:256
	s_nop 0
	v_add_f32_e32 v160, v162, v163
	ds_bpermute_b32 v147, v194, v146
	ds_bpermute_b32 v149, v194, v148
	ds_bpermute_b32 v151, v194, v150
	ds_bpermute_b32 v153, v194, v152
	ds_bpermute_b32 v155, v194, v154
	ds_bpermute_b32 v157, v194, v156
	ds_bpermute_b32 v159, v194, v158
	ds_bpermute_b32 v161, v194, v160
	s_waitcnt lgkmcnt(7)
	v_add_f32_e32 v146, v146, v147
	s_waitcnt lgkmcnt(6)
	v_add_f32_e32 v148, v148, v149
	s_waitcnt lgkmcnt(5)
	v_add_f32_e32 v150, v150, v151
	s_waitcnt lgkmcnt(4)
	v_add_f32_e32 v152, v152, v153
	s_waitcnt lgkmcnt(3)
	v_add_f32_e32 v154, v154, v155
	s_waitcnt lgkmcnt(2)
	v_add_f32_e32 v156, v156, v157
	s_waitcnt lgkmcnt(1)
	v_add_f32_e32 v158, v158, v159
	s_waitcnt lgkmcnt(0)
	v_add_f32_e32 v160, v160, v161
	ds_bpermute_b32 v147, v195, v146
	ds_bpermute_b32 v149, v195, v148
	ds_bpermute_b32 v151, v195, v150
	ds_bpermute_b32 v153, v195, v152
	ds_bpermute_b32 v155, v195, v154
	ds_bpermute_b32 v157, v195, v156
	ds_bpermute_b32 v159, v195, v158
	ds_bpermute_b32 v161, v195, v160
	s_waitcnt lgkmcnt(7)
	v_add_f32_e32 v146, v146, v147
	s_waitcnt lgkmcnt(6)
	v_add_f32_e32 v148, v148, v149
	s_waitcnt lgkmcnt(5)
	v_add_f32_e32 v150, v150, v151
	s_waitcnt lgkmcnt(4)
	v_add_f32_e32 v152, v152, v153
	s_waitcnt lgkmcnt(3)
	v_add_f32_e32 v154, v154, v155
	s_waitcnt lgkmcnt(2)
	v_add_f32_e32 v156, v156, v157
	s_waitcnt lgkmcnt(1)
	v_add_f32_e32 v158, v158, v159
	s_waitcnt lgkmcnt(0)
	v_add_f32_e32 v160, v160, v161
	s_and_saveexec_b64 s[88:89], s[0:1]
	global_store_dword v[240:241], v146, off
	global_store_dword v[240:241], v148, off offset:1024
	global_store_dword v[240:241], v150, off offset:2048
	global_store_dword v[240:241], v152, off offset:3072
	s_movk_i32 s84, 0x2000
	v_lshl_add_u64 v[240:241], v[240:241], 0, s[84:85]
	global_store_dword v[240:241], v154, off
	global_store_dword v[240:241], v156, off offset:1024
	global_store_dword v[240:241], v158, off offset:2048
	global_store_dword v[240:241], v160, off offset:3072
	s_or_b64 exec, exec, s[88:89]
	v_and_b32_e32 v56, 64, v246
	v_add_u32_e32 v56, 64, v56
	s_and_b64 vcc, exec, s[6:7]
	s_mov_b64 s[6:7], -1
	s_cbranch_vccnz .LBB0_1105
	s_andn2_b64 vcc, exec, s[20:21]
	s_cbranch_vccnz .LBB0_1104
	s_barrier
	s_branch .LBB0_1104
